# v85 + phase-10 RG-LRU tile: parameter-table pointers read once per block by scalar loads; gate-weight fragments and biases of j=1..3 prefetched into free VGPRs when j=0 is issued
# baseline (speedup 1.0000x reference)
.LBB0_1070:
	s_cmpk_gt_i32 s82, 0x1fff
	s_cbranch_scc1 .LBB0_1083
	s_add_u32 s8, s6, 0x2d500120
	s_addc_u32 s9, s7, 0
	s_add_u32 s0, s6, 0x2d500098
	s_addc_u32 s1, s7, 0
	s_add_u32 s10, s6, 0x2d5000b0
	s_addc_u32 s11, s7, 0
	s_add_u32 s12, s6, 0x2d5000c0
	s_addc_u32 s13, s7, 0
	v_mov_b64_e32 v[22:23], s[8:9]
	v_mov_b64_e32 v[24:25], s[0:1]
	s_load_dwordx4 s[64:67], s[0:1], 0x0
	s_load_dwordx2 s[68:69], s[8:9], 0x0
	s_load_dwordx4 s[72:75], s[12:13], 0x0
	s_load_dwordx2 s[70:71], s[10:11], 0x0
	s_waitcnt lgkmcnt(0)
	v_mov_b32_e32 v27, 0
	s_movk_i32 s2, 0x1200
	s_mov_b64 s[14:15], 0x4000e00
	s_brev_b32 s3, 32
	s_mov_b32 s17, 0
	s_movk_i32 s26, 0x1000
	s_movk_i32 s27, 0x104
	s_movk_i32 s28, 0x90
	s_movk_i32 s29, 0x7fff
	s_mov_b32 s30, 0x7060302
	s_mov_b64 s[18:19], 0x3608000
	s_mov_b64 s[20:21], 0x3618000
	s_mov_b32 s31, 0xbfb8aa3b
	s_mov_b32 s33, 0x3f2aaaab
	v_mov_b32_e32 v1, 0x3ecc95a3
	s_mov_b32 s34, 0x3f317218
	s_mov_b32 s35, 0x7f800000
	s_mov_b32 s36, 0x33800000
	s_movk_i32 s37, 0x41
	s_mov_b32 s41, 0x3fb8aa3b
	s_mov_b32 s42, 0xc2ce8ed0
	s_mov_b32 s43, 0x42b17218
	v_mov_b32_e32 v56, 0x3ab69700
	s_mov_b32 s44, 0x43000000
	s_mov_b32 s45, 0x42b17217
	s_mov_b32 s46, 0xf800000
	v_mov_b32_e32 v57, 0x260
	s_mov_b32 s47, 0xc1880000
	v_mov_b32_e32 v28, 0x3f317218
	v_mov_b32_e32 v58, 0x7f800000
	v_mov_b32_e32 v59, 0x7fc00000
	v_mov_b32_e32 v60, 0xff800000
	v_mov_b32_e32 v61, 0x7f000000
	s_mov_b32 s48, s82
	s_branch .LBB0_1073

.LBB0_1073:
	s_waitcnt vmcnt(0) lgkmcnt(0)
	v_mov_b32_e32 v30, v130
	v_mov_b32_e32 v18, s64
	v_mov_b32_e32 v19, s65
	v_mov_b32_e32 v20, s66
	v_mov_b32_e32 v21, s67
	v_mov_b32_e32 v32, s68
	v_mov_b32_e32 v33, s69
	s_and_b32 s16, s48, 7
	v_lshlrev_b32_e32 v2, 4, v30
	s_lshl_b32 s49, s16, 6
	v_and_b32_e32 v29, 48, v2
	v_or_b32_e32 v31, s49, v29
	v_lshlrev_b32_e32 v26, 2, v31
	s_bfe_u32 s50, s48, 0x70003
	s_ashr_i32 s22, s48, 10
	s_ashr_i32 s23, s22, 31
	s_lshl_b32 s24, s50, 6
	v_ashrrev_i32_e32 v34, 2, v30
	s_lshl_b64 s[0:1], s[22:23], 13
	s_not_b32 s23, s24
	s_or_b32 s0, s0, s24
	s_waitcnt vmcnt(0) lgkmcnt(0)
	v_lshl_add_u64 v[20:21], v[20:21], 0, v[26:27]
	flat_load_dwordx4 v[14:17], v[20:21]
	flat_load_dwordx4 v[10:13], v[20:21] offset:16
	flat_load_dwordx4 v[6:9], v[20:21] offset:32
	flat_load_dwordx4 v[2:5], v[20:21] offset:48
	v_add_u32_e32 v20, -3, v34
	v_lshl_add_u64 v[18:19], v[18:19], 0, v[26:27]
	v_cmp_lt_i32_e32 vcc, s23, v20
	v_lshlrev_b32_e32 v26, 1, v31
	s_and_saveexec_b64 s[24:25], vcc
	s_cbranch_execz .LBB0_1075
	v_ashrrev_i32_e32 v21, 31, v20
	v_lshl_add_u64 v[20:21], s[0:1], 0, v[20:21]
	v_mad_u64_u32 v[36:37], s[52:53], v20, s2, v[32:33]
	v_mov_b32_e32 v20, v37
	v_mad_u64_u32 v[20:21], s[52:53], v21, s2, v[20:21]
	v_mov_b32_e32 v37, v20
	v_lshl_add_u64 v[20:21], v[36:37], 0, v[26:27]
	v_add_co_u32_e32 v36, vcc, s3, v20
	s_nop 1
	v_addc_co_u32_e32 v37, vcc, 0, v21, vcc
	flat_load_dwordx4 v[36:39], v[36:37] offset:3584
	v_lshl_add_u64 v[20:21], v[20:21], 0, s[14:15]
	flat_load_dwordx4 v[40:43], v[20:21] offset:16
	flat_load_dwordx4 v[44:47], v[18:19] offset:16
	flat_load_dwordx4 v[48:51], v[18:19]
	flat_load_dwordx4 v[52:55], v[18:19] offset:48
	flat_load_dwordx4 v[62:65], v[18:19] offset:32
	s_waitcnt vmcnt(0) lgkmcnt(0)
	v_lshlrev_b32_e32 v68, 16, v40
	v_and_b32_e32 v69, 0xffff0000, v40
	v_lshlrev_b32_e32 v20, 16, v36
	v_and_b32_e32 v21, 0xffff0000, v36
	v_lshlrev_b32_e32 v36, 16, v37
	v_and_b32_e32 v37, 0xffff0000, v37
	v_lshlrev_b32_e32 v66, 16, v38
	v_and_b32_e32 v67, 0xffff0000, v38
	v_lshlrev_b32_e32 v38, 16, v39
	v_and_b32_e32 v39, 0xffff0000, v39
	v_lshlrev_b32_e32 v40, 16, v41
	v_and_b32_e32 v41, 0xffff0000, v41
	v_lshlrev_b32_e32 v70, 16, v42
	v_and_b32_e32 v71, 0xffff0000, v42
	v_lshlrev_b32_e32 v42, 16, v43
	v_and_b32_e32 v43, 0xffff0000, v43
	v_pk_fma_f32 v[12:13], v[46:47], v[38:39], v[12:13]
	v_pk_fma_f32 v[10:11], v[44:45], v[66:67], v[10:11]
	v_pk_fma_f32 v[16:17], v[50:51], v[36:37], v[16:17]
	v_pk_fma_f32 v[14:15], v[48:49], v[20:21], v[14:15]
	v_pk_fma_f32 v[4:5], v[54:55], v[42:43], v[4:5]
	v_pk_fma_f32 v[2:3], v[52:53], v[70:71], v[2:3]
	v_pk_fma_f32 v[8:9], v[64:65], v[40:41], v[8:9]
	v_pk_fma_f32 v[6:7], v[62:63], v[68:69], v[6:7]

.LBB0_1081:
	s_or_b64 exec, exec, s[24:25]
	v_mul_lo_u32 v18, v34, s27
	v_lshlrev_b32_e32 v19, 2, v29
	v_add3_u32 v18, 0, v18, v19
	v_mul_lo_u32 v19, v34, s28
	v_lshlrev_b32_e32 v20, 1, v29
	v_add3_u32 v19, 0, v19, v20
	s_waitcnt vmcnt(0) lgkmcnt(0)
	v_bfe_u32 v20, v17, 16, 1
	v_bfe_u32 v21, v16, 16, 1
	v_bfe_u32 v26, v15, 16, 1
	v_bfe_u32 v29, v14, 16, 1
	ds_write2_b32 v18, v14, v15 offset1:1
	ds_write2_b32 v18, v16, v17 offset0:2 offset1:3
	v_add3_u32 v14, v14, v29, s29
	v_add3_u32 v15, v15, v26, s29
	v_add3_u32 v16, v16, v21, s29
	v_add3_u32 v17, v17, v20, s29
	v_bfe_u32 v20, v13, 16, 1
	v_bfe_u32 v21, v12, 16, 1
	v_bfe_u32 v26, v11, 16, 1
	v_bfe_u32 v29, v10, 16, 1
	ds_write2_b32 v18, v10, v11 offset0:4 offset1:5
	ds_write2_b32 v18, v12, v13 offset0:6 offset1:7
	v_add3_u32 v10, v10, v29, s29
	v_add3_u32 v11, v11, v26, s29
	v_add3_u32 v12, v12, v21, s29
	v_add3_u32 v13, v13, v20, s29
	v_perm_b32 v13, v13, v12, s30
	v_perm_b32 v12, v11, v10, s30
	v_perm_b32 v11, v17, v16, s30
	v_perm_b32 v10, v15, v14, s30
	ds_write_b128 v19, v[10:13] offset:16640
	ds_write2_b32 v18, v6, v7 offset0:8 offset1:9
	ds_write2_b32 v18, v8, v9 offset0:10 offset1:11
	v_bfe_u32 v10, v9, 16, 1
	v_bfe_u32 v11, v8, 16, 1
	v_bfe_u32 v12, v7, 16, 1
	v_bfe_u32 v13, v6, 16, 1
	v_add3_u32 v6, v6, v13, s29
	v_add3_u32 v7, v7, v12, s29
	v_add3_u32 v8, v8, v11, s29
	v_add3_u32 v9, v9, v10, s29
	v_bfe_u32 v10, v5, 16, 1
	v_bfe_u32 v11, v4, 16, 1
	v_bfe_u32 v12, v3, 16, 1
	v_bfe_u32 v13, v2, 16, 1
	ds_write2_b32 v18, v2, v3 offset0:12 offset1:13
	ds_write2_b32 v18, v4, v5 offset0:14 offset1:15
	v_add3_u32 v2, v2, v13, s29
	v_add3_u32 v3, v3, v12, s29
	v_add3_u32 v4, v4, v11, s29
	v_add3_u32 v5, v5, v10, s29
	v_perm_b32 v5, v5, v4, s30
	v_perm_b32 v4, v3, v2, s30
	v_perm_b32 v3, v9, v8, s30
	v_perm_b32 v2, v7, v6, s30
	ds_write_b128 v19, v[2:5] offset:16656
	v_mov_b64_e32 v[2:3], s[8:9]
	s_waitcnt lgkmcnt(0)
	s_barrier
	v_mov_b32_e32 v2, s68
	v_mov_b32_e32 v3, s69
	v_mov_b64_e32 v[4:5], s[12:13]
	v_mov_b32_e32 v10, s72
	v_mov_b32_e32 v11, s73
	v_mov_b32_e32 v12, s74
	v_mov_b32_e32 v13, s75
	v_mov_b64_e32 v[4:5], s[10:11]
	v_mov_b32_e32 v40, s70
	v_mov_b32_e32 v41, s71
	s_lshl_b32 s16, s16, 13
	v_bfi_b32 v4, -16, v34, v30
	v_and_b32_e32 v26, 48, v30
	v_and_b32_e32 v42, 15, v30
	v_mul_lo_u32 v4, v4, s28
	v_or_b32_e32 v6, s49, v42
	v_add3_u32 v29, 0, v4, v26
	v_mov_b32_e32 v5, v27
	v_lshlrev_b32_e32 v4, 2, v6
	v_and_b32_e32 v31, -16, v34
	v_lshrrev_b32_e32 v48, 2, v30
	v_and_or_b32 v51, v48, 12, v31
	s_waitcnt vmcnt(0) lgkmcnt(0)
	v_lshl_add_u64 v[2:3], v[2:3], 0, s[16:17]
	v_lshl_add_u64 v[2:3], v[2:3], 0, v[26:27]
	v_lshlrev_b32_e32 v26, 7, v42
	v_lshl_add_u64 v[36:37], v[2:3], 0, s[18:19]
	v_lshl_add_u64 v[46:47], v[36:37], 0, v[26:27]
	v_lshl_add_u64 v[6:7], v[12:13], 0, v[4:5]
	flat_load_dwordx4 v[14:17], v[46:47]
	flat_load_dword v35, v[6:7]
	v_lshl_add_u64 v[38:39], v[2:3], 0, s[20:21]
	v_lshl_add_u64 v[44:45], v[38:39], 0, v[26:27]
	flat_load_dwordx4 v[18:21], v[44:45]
	flat_load_dwordx4 v[52:55], v[46:47] offset:64
	flat_load_dwordx4 v[62:65], v[44:45] offset:64
	v_lshl_add_u64 v[2:3], v[40:41], 0, v[4:5]
	v_lshl_add_u64 v[4:5], v[10:11], 0, v[4:5]
	flat_load_dword v43, v[2:3]
	flat_load_dword v50, v[4:5]
	global_load_dwordx4 v[132:135], v[46:47], off offset:2048
	global_load_dwordx4 v[136:139], v[46:47], off offset:2112
	global_load_dwordx4 v[140:143], v[44:45], off offset:2048
	global_load_dwordx4 v[144:147], v[44:45], off offset:2112
	s_mov_b32 s98, 0x1000
	s_mov_b32 s99, 0
	v_lshl_add_u64 v[96:97], v[46:47], 0, s[98:99]
	v_lshl_add_u64 v[98:99], v[44:45], 0, s[98:99]
	global_load_dwordx4 v[148:151], v[96:97], off
	global_load_dwordx4 v[152:155], v[96:97], off offset:64
	global_load_dwordx4 v[156:159], v[98:99], off
	global_load_dwordx4 v[160:163], v[98:99], off offset:64
	global_load_dwordx4 v[164:167], v[96:97], off offset:2048
	global_load_dwordx4 v[168:171], v[96:97], off offset:2112
	global_load_dwordx4 v[172:175], v[98:99], off offset:2048
	global_load_dwordx4 v[176:179], v[98:99], off offset:2112
	global_load_dword v180, v[6:7], off offset:64
	global_load_dword v181, v[4:5], off offset:64
	global_load_dword v182, v[2:3], off offset:64
	global_load_dword v183, v[6:7], off offset:128
	global_load_dword v184, v[4:5], off offset:128
	global_load_dword v185, v[2:3], off offset:128
	global_load_dword v186, v[6:7], off offset:192
	global_load_dword v187, v[4:5], off offset:192
	global_load_dword v188, v[2:3], off offset:192
	ds_read_b128 v[6:9], v29 offset:16640
	ds_read_b128 v[2:5], v29 offset:16704
	s_waitcnt vmcnt(0) lgkmcnt(0)
	v_mfma_f32_16x16x32_bf16 v[18:21], v[6:9], v[18:21], 0
	v_mul_f32_e64 v29, |v35|, s31
	v_exp_f32_e32 v72, v29
	v_max_f32_e64 v29, -v35, -v35
	v_mfma_f32_16x16x32_bf16 v[14:17], v[6:9], v[14:17], 0
	v_max_f32_e32 v35, 0, v29
	v_add_f32_e32 v29, 1.0, v72
	v_cvt_f64_f32_e32 v[48:49], v29
	v_mfma_f32_16x16x32_bf16 v[14:17], v[2:5], v[52:55], v[14:17]
	v_add_f32_e32 v52, -1.0, v29
	v_frexp_mant_f32_e32 v53, v29
	v_sub_f32_e32 v54, v52, v29
	v_frexp_exp_i32_f64_e32 v48, v[48:49]
	v_cmp_gt_f32_e32 vcc, s33, v53
	v_mfma_f32_16x16x32_bf16 v[18:21], v[2:5], v[62:65], v[18:21]
	v_sub_f32_e32 v52, v72, v52
	v_add_f32_e32 v49, 1.0, v54
	v_subbrev_co_u32_e32 v48, vcc, 0, v48, vcc
	v_add_f32_e32 v49, v52, v49
	v_sub_u32_e32 v52, 0, v48
	v_ldexp_f32 v29, v29, v52
	v_ldexp_f32 v49, v49, v52
	v_add_f32_e32 v52, -1.0, v29
	v_add_f32_e32 v54, 1.0, v29
	v_add_f32_e32 v14, v14, v43
	v_add_f32_e32 v18, v18, v50
	v_add_f32_e32 v53, 1.0, v52
	v_add_f32_e32 v55, -1.0, v54
	v_mul_f32_e32 v14, 0xbfb8aa3b, v14
	v_mul_f32_e32 v18, 0xbfb8aa3b, v18
	v_sub_f32_e32 v62, v29, v53
	v_sub_f32_e32 v29, v29, v55
	v_exp_f32_e32 v53, v14
	v_exp_f32_e32 v14, v18
	v_add_f32_e32 v29, v49, v29
	v_add_f32_e32 v18, v49, v62
	v_add_f32_e32 v49, v54, v29
	v_add_f32_e32 v55, v52, v18
	v_rcp_f32_e32 v66, v49
	v_sub_f32_e32 v52, v55, v52
	v_sub_f32_e32 v18, v18, v52
	v_add_f32_e32 v52, 1.0, v14
	v_div_scale_f32 v14, s[0:1], v52, v52, 1.0
	v_rcp_f32_e32 v68, v14
	v_mul_f32_e32 v69, v55, v66
	v_sub_f32_e32 v54, v49, v54
	v_mul_f32_e32 v62, v49, v69
	v_sub_f32_e32 v29, v29, v54
	v_fma_f32 v64, v69, v49, -v62
	v_fmac_f32_e32 v64, v69, v29
	v_fma_f32 v63, -v14, v68, 1.0
	v_add_f32_e32 v54, v62, v64
	v_fmac_f32_e32 v68, v63, v68
	v_sub_f32_e32 v63, v55, v54
	v_div_scale_f32 v67, vcc, 1.0, v52, 1.0
	v_mov_b32_e32 v65, v54
	v_pk_add_f32 v[54:55], v[54:55], v[62:63] neg_lo:[0,1] neg_hi:[0,1]
	v_mul_f32_e32 v70, v67, v68
	v_pk_add_f32 v[54:55], v[54:55], v[64:65] neg_lo:[0,1] neg_hi:[0,1]
	v_fma_f32 v62, -v14, v70, v67
	v_add_f32_e32 v18, v18, v55
	v_fmac_f32_e32 v70, v62, v68
	v_add_f32_e32 v18, v54, v18
	v_fma_f32 v14, -v14, v70, v67
	v_add_f32_e32 v55, v63, v18
	v_div_fmas_f32 v73, v14, v68, v70
	v_mul_f32_e32 v14, v66, v55
	v_mul_f32_e32 v62, v49, v14
	v_fma_f32 v64, v14, v49, -v62
	v_sub_f32_e32 v54, v63, v55
	v_fmac_f32_e32 v64, v14, v29
	v_add_f32_e32 v18, v18, v54
	v_add_f32_e32 v54, v62, v64
	v_sub_f32_e32 v63, v55, v54
	v_mov_b32_e32 v65, v54
	v_pk_add_f32 v[54:55], v[54:55], v[62:63] neg_lo:[0,1] neg_hi:[0,1]
	v_add_f32_e32 v67, v69, v14
	v_pk_add_f32 v[54:55], v[54:55], v[64:65] neg_lo:[0,1] neg_hi:[0,1]
	v_sub_f32_e32 v49, v67, v69
	v_add_f32_e32 v18, v18, v55
	v_add_f32_e32 v18, v54, v18
	v_add_f32_e32 v18, v63, v18
	v_sub_f32_e32 v14, v14, v49
	v_mul_f32_e32 v18, v66, v18
	v_add_f32_e32 v14, v14, v18
	v_cvt_f32_i32_e32 v48, v48
	v_add_f32_e32 v18, v67, v14
	v_mul_f32_e32 v29, v18, v18
	v_sub_f32_e32 v49, v18, v67
	v_fmamk_f32 v54, v29, 0x3e9b6dac, v1
	v_sub_f32_e32 v14, v14, v49
	v_mul_f32_e32 v49, v18, v29
	v_fmaak_f32 v29, v29, v54, 0x3f2aaada
	v_pk_mul_f32 v[62:63], v[48:49], v[28:29]
	v_ldexp_f32 v55, v18, 1
	v_fma_f32 v54, v48, s34, -v62
	v_fmac_f32_e32 v54, 0xb102e308, v48
	v_pk_add_f32 v[48:49], v[62:63], v[54:55]
	v_ldexp_f32 v14, v14, 1
	v_sub_f32_e32 v18, v49, v55
	v_sub_f32_e32 v18, v63, v18
	v_mov_b32_e32 v64, v62
	v_add_f32_e32 v65, v14, v18
	v_pk_add_f32 v[66:67], v[48:49], v[62:63] neg_lo:[0,1] neg_hi:[0,1]
	v_pk_add_f32 v[62:63], v[48:49], v[64:65]
	v_mov_b32_e32 v55, v48
	v_mov_b32_e32 v67, v63
	v_pk_add_f32 v[70:71], v[54:55], v[66:67] neg_lo:[0,1] neg_hi:[0,1]
	v_pk_add_f32 v[54:55], v[54:55], v[66:67]
	v_mov_b32_e32 v69, v48
	v_pk_add_f32 v[66:67], v[54:55], v[48:49] op_sel:[1,0] op_sel_hi:[0,1] neg_lo:[0,1] neg_hi:[0,1]
	v_mov_b32_e32 v68, v65
	v_mov_b32_e32 v64, v63
	v_mov_b32_e32 v65, v55
	v_pk_mov_b32 v[48:49], v[48:49], v[66:67] op_sel:[1,0]
	v_pk_add_f32 v[62:63], v[62:63], v[66:67] op_sel_hi:[1,0] neg_lo:[0,1] neg_hi:[0,1]
	v_pk_add_f32 v[48:49], v[64:65], v[48:49] neg_lo:[0,1] neg_hi:[0,1]
	v_mov_b32_e32 v62, v70
	v_pk_add_f32 v[48:49], v[68:69], v[48:49] neg_lo:[0,1] neg_hi:[0,1]
	v_mov_b32_e32 v71, v55
	v_pk_add_f32 v[62:63], v[62:63], v[48:49]
	v_add_f32_e32 v18, v19, v50
	v_pk_add_f32 v[64:65], v[62:63], v[62:63] op_sel:[0,1] op_sel_hi:[1,0]
	v_mul_f32_e32 v18, 0xbfb8aa3b, v18
	v_pk_add_f32 v[54:55], v[54:55], v[64:65] op_sel:[1,0] op_sel_hi:[0,1]
	v_mov_b32_e32 v63, v54
	v_mov_b32_e32 v49, v64
	v_pk_add_f32 v[64:65], v[62:63], v[70:71] neg_lo:[0,1] neg_hi:[0,1]
	v_exp_f32_e32 v29, v18
	v_sub_f32_e32 v14, v62, v64
	v_pk_add_f32 v[48:49], v[48:49], v[64:65] neg_lo:[0,1] neg_hi:[0,1]
	v_sub_f32_e32 v14, v70, v14
	v_add_f32_e32 v14, v48, v14
	v_add_f32_e32 v14, v14, v49
	v_add_f32_e32 v14, v54, v14
	v_cmp_neq_f32_e32 vcc, s35, v72
	v_mad_u64_u32 v[18:19], s[0:1], v51, s37, v[42:43]
	s_nop 0
	v_cndmask_b32_e32 v14, v58, v14, vcc
	v_cmp_ngt_f32_e32 vcc, -1.0, v72
	v_add_f32_e32 v19, 1.0, v29
	v_div_scale_f32 v29, s[0:1], v19, v19, 1.0
	v_cndmask_b32_e32 v14, v59, v14, vcc
	v_cmp_neq_f32_e32 vcc, -1.0, v72
	v_add_f32_e32 v15, v15, v43
	v_mul_f32_e32 v15, 0xbfb8aa3b, v15
	v_cndmask_b32_e32 v14, v60, v14, vcc
	v_cmp_lt_f32_e64 vcc, |v72|, s36
	v_div_fixup_f32 v54, v73, v52, 1.0
	v_exp_f32_e32 v52, v15
	v_cndmask_b32_e32 v14, v14, v72, vcc
	v_add_f32_e32 v14, v35, v14
	v_rcp_f32_e32 v35, v29
	v_mul_f32_e32 v14, 0xc1000000, v14
	v_add_f32_e32 v16, v16, v43
	v_mul_f32_e32 v16, 0xbfb8aa3b, v16
	v_fma_f32 v15, -v29, v35, 1.0
	v_fmac_f32_e32 v35, v15, v35
	v_div_scale_f32 v15, vcc, 1.0, v19, 1.0
	v_mul_f32_e32 v51, v15, v35
	v_fma_f32 v48, -v29, v51, v15
	v_fmac_f32_e32 v51, v48, v35
	v_pk_add_f32 v[48:49], v[52:53], 1.0 op_sel_hi:[1,0]
	v_fma_f32 v15, -v29, v51, v15
	v_div_scale_f32 v52, s[0:1], v49, v49, 1.0
	v_rcp_f32_e32 v53, v52
	v_div_fmas_f32 v15, v15, v35, v51
	v_add_f32_e32 v21, v21, v50
	v_mul_f32_e32 v21, 0xbfb8aa3b, v21
	v_fma_f32 v29, -v52, v53, 1.0
	v_fmac_f32_e32 v53, v29, v53
	v_div_scale_f32 v29, vcc, 1.0, v49, 1.0
	v_mul_f32_e32 v35, v29, v53
	v_fma_f32 v51, -v52, v35, v29
	v_fmac_f32_e32 v35, v51, v53
	v_div_scale_f32 v51, s[0:1], v48, v48, 1.0
	v_fma_f32 v29, -v52, v35, v29
	v_rcp_f32_e32 v52, v51
	v_div_fmas_f32 v29, v29, v53, v35
	v_div_fixup_f32 v49, v29, v49, 1.0
	v_exp_f32_e32 v21, v21
	v_fma_f32 v29, -v51, v52, 1.0
	v_fmac_f32_e32 v52, v29, v52
	v_div_scale_f32 v29, vcc, 1.0, v48, 1.0
	v_mul_f32_e32 v35, v29, v52
	v_fma_f32 v53, -v51, v35, v29
	v_fmac_f32_e32 v35, v53, v52
	v_fma_f32 v29, -v51, v35, v29
	v_div_fmas_f32 v29, v29, v52, v35
	v_div_fixup_f32 v48, v29, v48, 1.0
	v_pk_mul_f32 v[52:53], v[48:49], v[14:15] op_sel_hi:[1,0]
	v_div_fixup_f32 v15, v15, v19, 1.0
	v_mul_f32_e32 v29, 0x3fb8aa3b, v53
	v_fma_f32 v35, v53, s41, -v29
	v_rndne_f32_e32 v48, v29
	v_fmac_f32_e32 v35, 0x32a5705f, v53
	v_sub_f32_e32 v29, v29, v48
	v_add_f32_e32 v29, v29, v35
	v_exp_f32_e32 v29, v29
	v_cvt_i32_f32_e32 v51, v48
	v_lshl_add_u32 v35, v18, 2, 0
	v_cmp_ngt_f32_e32 vcc, s42, v53
	v_cmp_nlt_f32_e64 s[0:1], s43, v53
	v_ldexp_f32 v18, v29, v51
	v_cndmask_b32_e32 v29, 0, v18, vcc
	v_pk_add_f32 v[18:19], v[52:53], v[52:53]
	v_cndmask_b32_e64 v29, v58, v29, s[0:1]
	v_mul_f32_e32 v51, 0x3fb8aa3b, v19
	v_rndne_f32_e32 v51, v51
	v_fmamk_f32 v55, v51, 0xbf317218, v19
	v_fmac_f32_e32 v55, 0x3102e308, v51
	v_fmamk_f32 v62, v55, 0x395133b1, v56
	v_fmaak_f32 v62, v55, v62, 0x3c0887f9
	v_fmaak_f32 v62, v55, v62, 0x3d2aaa81
	v_cvt_i32_f32_e32 v63, v51
	v_fmaak_f32 v62, v55, v62, 0x3e2aaaab
	v_fma_f32 v62, v55, v62, 0.5
	v_mul_f32_e32 v62, v55, v62
	v_fmac_f32_e32 v55, v55, v62
	v_ldexp_f32 v62, 1.0, v63
	v_cmp_eq_f32_e32 vcc, s44, v51
	ds_write_b32 v35, v29 offset:25856
	ds_read2_b32 v[48:49], v35 offset1:16
	v_cndmask_b32_e32 v51, v62, v61, vcc
	v_add_f32_e32 v62, -1.0, v51
	v_fmac_f32_e32 v62, v51, v55
	v_add_f32_e32 v51, v62, v62
	v_cndmask_b32_e32 v51, v62, v51, vcc
	v_cmp_nlt_f32_e32 vcc, s45, v19
	v_add_f32_e32 v21, 1.0, v21
	s_nop 0
	v_cndmask_b32_e64 v51, v60, -v51, vcc
	v_mul_f32_e32 v55, 0x4f800000, v51
	v_cmp_gt_f32_e32 vcc, s46, v51
	s_nop 1
	v_cndmask_b32_e32 v51, v51, v55, vcc
	v_sqrt_f32_e32 v55, v51
	s_nop 0
	v_add_u32_e32 v29, -1, v55
	v_fma_f32 v53, -v29, v55, v51
	v_cmp_ge_f32_e64 s[0:1], 0, v53
	v_add_u32_e32 v53, 1, v55
	s_nop 0
	v_cndmask_b32_e64 v29, v55, v29, s[0:1]
	v_fma_f32 v55, -v53, v55, v51
	v_cmp_lt_f32_e64 s[0:1], 0, v55
	s_nop 1
	v_cndmask_b32_e64 v29, v29, v53, s[0:1]
	v_mul_f32_e32 v53, 0x37800000, v29
	v_cndmask_b32_e32 v29, v29, v53, vcc
	v_cmp_class_f32_e32 vcc, v51, v57
	v_cmp_nlt_f32_e64 s[0:1], s43, v52
	s_nop 0
	v_cndmask_b32_e32 v29, v29, v51, vcc
	v_cmp_ngt_f32_e32 vcc, s47, v19
	s_nop 1
	v_cndmask_b32_e32 v19, 1.0, v29, vcc
	v_mul_f32_e32 v29, 0x3fb8aa3b, v52
	v_fma_f32 v51, v52, s41, -v29
	v_rndne_f32_e32 v53, v29
	v_fmac_f32_e32 v51, 0x32a5705f, v52
	v_sub_f32_e32 v29, v29, v53
	v_add_f32_e32 v29, v29, v51
	v_exp_f32_e32 v29, v29
	v_cvt_i32_f32_e32 v51, v53
	v_mul_f32_e32 v19, v54, v19
	s_waitcnt lgkmcnt(0)
	v_mul_f32_e32 v19, v48, v19
	ds_write_b32 v35, v19 offset:42496
	v_ldexp_f32 v19, v29, v51
	v_mul_f32_e32 v29, 0x3fb8aa3b, v18
	v_rndne_f32_e32 v29, v29
	v_fmamk_f32 v48, v29, 0xbf317218, v18
	v_fmac_f32_e32 v48, 0x3102e308, v29
	v_fmamk_f32 v51, v48, 0x395133b1, v56
	v_fmaak_f32 v51, v48, v51, 0x3c0887f9
	v_fmaak_f32 v51, v48, v51, 0x3d2aaa81
	v_cvt_i32_f32_e32 v53, v29
	v_fmaak_f32 v51, v48, v51, 0x3e2aaaab
	v_fma_f32 v51, v48, v51, 0.5
	v_cmp_ngt_f32_e32 vcc, s42, v52
	v_mul_f32_e32 v51, v48, v51
	v_fmac_f32_e32 v48, v48, v51
	v_cndmask_b32_e32 v19, 0, v19, vcc
	v_ldexp_f32 v51, 1.0, v53
	v_cmp_eq_f32_e32 vcc, s44, v29
	v_cndmask_b32_e64 v19, v58, v19, s[0:1]
	ds_write_b32 v35, v19 offset:26116
	v_cndmask_b32_e32 v29, v51, v61, vcc
	v_add_f32_e32 v51, -1.0, v29
	v_fmac_f32_e32 v51, v29, v48
	v_add_f32_e32 v29, v51, v51
	v_cndmask_b32_e32 v29, v51, v29, vcc
	v_cmp_nlt_f32_e32 vcc, s45, v18
	ds_read2_b32 v[52:53], v35 offset0:65 offset1:81
	s_nop 0
	v_cndmask_b32_e64 v29, v60, -v29, vcc
	v_mul_f32_e32 v48, 0x4f800000, v29
	v_cmp_gt_f32_e32 vcc, s46, v29
	s_nop 1
	v_cndmask_b32_e32 v29, v29, v48, vcc
	v_sqrt_f32_e32 v48, v29
	s_nop 0
	v_add_u32_e32 v19, -1, v48
	v_fma_f32 v51, -v19, v48, v29
	v_cmp_ge_f32_e64 s[0:1], 0, v51
	v_add_u32_e32 v51, 1, v48
	s_nop 0
	v_cndmask_b32_e64 v19, v48, v19, s[0:1]
	v_fma_f32 v48, -v51, v48, v29
	v_cmp_lt_f32_e64 s[0:1], 0, v48
	s_nop 1
	v_cndmask_b32_e64 v19, v19, v51, s[0:1]
	v_mul_f32_e32 v48, 0x37800000, v19
	v_cndmask_b32_e32 v19, v19, v48, vcc
	v_cmp_class_f32_e32 vcc, v29, v57
	s_nop 1
	v_cndmask_b32_e32 v19, v19, v29, vcc
	v_cmp_ngt_f32_e32 vcc, s47, v18
	s_nop 1
	v_cndmask_b32_e32 v18, 1.0, v19, vcc
	v_add_f32_e32 v19, v20, v50
	v_mul_f32_e32 v19, 0xbfb8aa3b, v19
	v_exp_f32_e32 v19, v19
	v_mul_f32_e32 v15, v15, v18
	s_waitcnt lgkmcnt(0)
	v_mul_f32_e32 v15, v52, v15
	ds_write_b32 v35, v15 offset:42756
	v_add_f32_e32 v20, 1.0, v19
	v_div_scale_f32 v15, s[0:1], v20, v20, 1.0
	v_rcp_f32_e32 v18, v15
	v_exp_f32_e32 v19, v16
	v_fma_f32 v16, -v15, v18, 1.0
	v_fmac_f32_e32 v18, v16, v18
	v_div_scale_f32 v16, vcc, 1.0, v20, 1.0
	v_mul_f32_e32 v29, v16, v18
	v_fma_f32 v48, -v15, v29, v16
	v_fmac_f32_e32 v29, v48, v18
	v_fma_f32 v15, -v15, v29, v16
	v_div_fmas_f32 v29, v15, v18, v29
	v_div_scale_f32 v15, s[0:1], v21, v21, 1.0
	v_rcp_f32_e32 v48, v15
	v_add_f32_e32 v16, v17, v43
	v_mul_f32_e32 v16, 0xbfb8aa3b, v16
	v_exp_f32_e32 v18, v16
	v_fma_f32 v16, -v15, v48, 1.0
	v_fmac_f32_e32 v48, v16, v48
	v_div_scale_f32 v43, vcc, 1.0, v21, 1.0
	v_mul_f32_e32 v50, v43, v48
	v_fma_f32 v16, -v15, v50, v43
	v_fmac_f32_e32 v50, v16, v48
	v_pk_add_f32 v[16:17], v[18:19], 1.0 op_sel_hi:[1,0]
	v_fma_f32 v15, -v15, v50, v43
	v_div_scale_f32 v18, s[0:1], v17, v17, 1.0
	v_rcp_f32_e32 v19, v18
	v_div_fmas_f32 v43, v15, v48, v50
	v_fma_f32 v15, -v18, v19, 1.0
	v_fmac_f32_e32 v19, v15, v19
	v_div_scale_f32 v15, vcc, 1.0, v17, 1.0
	v_mul_f32_e32 v48, v15, v19
	v_fma_f32 v50, -v18, v48, v15
	v_fmac_f32_e32 v48, v50, v19
	v_fma_f32 v15, -v18, v48, v15
	v_div_scale_f32 v18, s[0:1], v16, v16, 1.0
	v_rcp_f32_e32 v50, v18
	v_div_fmas_f32 v15, v15, v19, v48
	v_div_fixup_f32 v17, v15, v17, 1.0
	v_fma_f32 v15, -v18, v50, 1.0
	v_fmac_f32_e32 v50, v15, v50
	v_div_scale_f32 v15, vcc, 1.0, v16, 1.0
	v_mul_f32_e32 v19, v15, v50
	v_fma_f32 v48, -v18, v19, v15
	v_fmac_f32_e32 v19, v48, v50
	v_fma_f32 v15, -v18, v19, v15
	v_div_fmas_f32 v15, v15, v50, v19
	v_div_fixup_f32 v16, v15, v16, 1.0
	v_pk_mul_f32 v[14:15], v[16:17], v[14:15] op_sel_hi:[1,0]
	v_div_fixup_f32 v19, v43, v21, 1.0
	v_mul_f32_e32 v16, 0x3fb8aa3b, v15
	v_fma_f32 v17, v15, s41, -v16
	v_rndne_f32_e32 v18, v16
	v_fmac_f32_e32 v17, 0x32a5705f, v15
	v_sub_f32_e32 v16, v16, v18
	v_add_f32_e32 v16, v16, v17
	v_exp_f32_e32 v16, v16
	v_cvt_i32_f32_e32 v17, v18
	v_cmp_ngt_f32_e32 vcc, s42, v15
	v_div_fixup_f32 v18, v29, v20, 1.0
	v_cmp_nlt_f32_e64 s[0:1], s43, v15
	v_ldexp_f32 v16, v16, v17
	v_cndmask_b32_e32 v20, 0, v16, vcc
	v_pk_add_f32 v[16:17], v[14:15], v[14:15]
	v_cndmask_b32_e64 v15, v58, v20, s[0:1]
	v_mul_f32_e32 v21, 0x3fb8aa3b, v17
	v_rndne_f32_e32 v21, v21
	v_fmamk_f32 v29, v21, 0xbf317218, v17
	v_fmac_f32_e32 v29, 0x3102e308, v21
	v_fmamk_f32 v43, v29, 0x395133b1, v56
	v_fmaak_f32 v43, v29, v43, 0x3c0887f9
	v_fmaak_f32 v43, v29, v43, 0x3d2aaa81
	v_cvt_i32_f32_e32 v48, v21
	v_fmaak_f32 v43, v29, v43, 0x3e2aaaab
	v_fma_f32 v43, v29, v43, 0.5
	v_mul_f32_e32 v43, v29, v43
	v_fmac_f32_e32 v29, v29, v43
	v_ldexp_f32 v43, 1.0, v48
	v_cmp_eq_f32_e32 vcc, s44, v21
	ds_read2_b32 v[50:51], v35 offset0:130 offset1:146
	ds_write_b32 v35, v15 offset:26376
	v_cndmask_b32_e32 v21, v43, v61, vcc
	v_add_f32_e32 v43, -1.0, v21
	v_fmac_f32_e32 v43, v21, v29
	v_add_f32_e32 v21, v43, v43
	v_cndmask_b32_e32 v21, v43, v21, vcc
	v_cmp_nlt_f32_e32 vcc, s45, v17
	s_nop 1
	v_cndmask_b32_e64 v21, v60, -v21, vcc
	v_mul_f32_e32 v29, 0x4f800000, v21
	v_cmp_gt_f32_e32 vcc, s46, v21
	s_nop 1
	v_cndmask_b32_e32 v21, v21, v29, vcc
	v_sqrt_f32_e32 v29, v21
	s_nop 0
	v_add_u32_e32 v15, -1, v29
	v_fma_f32 v20, -v15, v29, v21
	v_cmp_ge_f32_e64 s[0:1], 0, v20
	v_add_u32_e32 v20, 1, v29
	s_nop 0
	v_cndmask_b32_e64 v15, v29, v15, s[0:1]
	v_fma_f32 v29, -v20, v29, v21
	v_cmp_lt_f32_e64 s[0:1], 0, v29
	s_nop 1
	v_cndmask_b32_e64 v15, v15, v20, s[0:1]
	v_mul_f32_e32 v20, 0x37800000, v15
	v_cndmask_b32_e32 v15, v15, v20, vcc
	v_cmp_class_f32_e32 vcc, v21, v57
	v_cmp_nlt_f32_e64 s[0:1], s43, v14
	s_nop 0
	v_cndmask_b32_e32 v15, v15, v21, vcc
	v_cmp_ngt_f32_e32 vcc, s47, v17
	v_mul_f32_e32 v17, 0x3fb8aa3b, v14
	v_fma_f32 v20, v14, s41, -v17
	v_rndne_f32_e32 v21, v17
	v_fmac_f32_e32 v20, 0x32a5705f, v14
	v_sub_f32_e32 v17, v17, v21
	v_add_f32_e32 v17, v17, v20
	v_exp_f32_e32 v17, v17
	v_cvt_i32_f32_e32 v20, v21
	v_cndmask_b32_e32 v15, 1.0, v15, vcc
	v_mul_f32_e32 v15, v18, v15
	s_waitcnt lgkmcnt(1)
	v_mul_f32_e32 v15, v50, v15
	ds_write_b32 v35, v15 offset:43016
	v_ldexp_f32 v15, v17, v20
	v_mul_f32_e32 v17, 0x3fb8aa3b, v16
	v_rndne_f32_e32 v17, v17
	v_fmamk_f32 v18, v17, 0xbf317218, v16
	v_fmac_f32_e32 v18, 0x3102e308, v17
	v_fmamk_f32 v20, v18, 0x395133b1, v56
	v_fmaak_f32 v20, v18, v20, 0x3c0887f9
	v_fmaak_f32 v20, v18, v20, 0x3d2aaa81
	v_cvt_i32_f32_e32 v21, v17
	v_fmaak_f32 v20, v18, v20, 0x3e2aaaab
	v_fma_f32 v20, v18, v20, 0.5
	v_cmp_ngt_f32_e32 vcc, s42, v14
	v_mul_f32_e32 v20, v18, v20
	v_fmac_f32_e32 v18, v18, v20
	v_cndmask_b32_e32 v15, 0, v15, vcc
	v_ldexp_f32 v20, 1.0, v21
	v_cmp_eq_f32_e32 vcc, s44, v17
	v_cndmask_b32_e64 v14, v58, v15, s[0:1]
	ds_write_b32 v35, v14 offset:26636
	v_cndmask_b32_e32 v17, v20, v61, vcc
	v_add_f32_e32 v20, -1.0, v17
	v_fmac_f32_e32 v20, v17, v18
	v_add_f32_e32 v17, v20, v20
	v_cndmask_b32_e32 v17, v20, v17, vcc
	v_cmp_nlt_f32_e32 vcc, s45, v16
	ds_read2_b32 v[54:55], v35 offset0:195 offset1:211
	s_nop 0
	v_cndmask_b32_e64 v17, v60, -v17, vcc
	v_mul_f32_e32 v18, 0x4f800000, v17
	v_cmp_gt_f32_e32 vcc, s46, v17
	s_nop 1
	v_cndmask_b32_e32 v17, v17, v18, vcc
	v_sqrt_f32_e32 v18, v17
	s_nop 0
	v_add_u32_e32 v14, -1, v18
	v_fma_f32 v15, -v14, v18, v17
	v_cmp_ge_f32_e64 s[0:1], 0, v15
	v_add_u32_e32 v15, 1, v18
	s_nop 0
	v_cndmask_b32_e64 v14, v18, v14, s[0:1]
	v_fma_f32 v18, -v15, v18, v17
	v_cmp_lt_f32_e64 s[0:1], 0, v18
	s_nop 1
	v_cndmask_b32_e64 v14, v14, v15, s[0:1]
	v_mul_f32_e32 v15, 0x37800000, v14
	v_cndmask_b32_e32 v14, v14, v15, vcc
	v_cmp_class_f32_e32 vcc, v17, v57
	s_nop 1
	v_cndmask_b32_e32 v14, v14, v17, vcc
	v_cmp_ngt_f32_e32 vcc, s47, v16
	s_nop 1
	v_cndmask_b32_e32 v14, 1.0, v14, vcc
	v_mul_f32_e32 v14, v19, v14
	s_waitcnt lgkmcnt(0)
	v_mul_f32_e32 v14, v54, v14
	ds_write_b32 v35, v14 offset:43276
	s_nop 0
	s_nop 0
	s_nop 0
	s_nop 0
	s_waitcnt vmcnt(0) lgkmcnt(0)
	v_mov_b32_e32 v14, v132
	v_mov_b32_e32 v15, v133
	v_mov_b32_e32 v16, v134
	v_mov_b32_e32 v17, v135
	v_mov_b32_e32 v18, v136
	v_mov_b32_e32 v19, v137
	v_mov_b32_e32 v20, v138
	v_mov_b32_e32 v21, v139
	v_mov_b32_e32 v62, v140
	v_mov_b32_e32 v63, v141
	v_mov_b32_e32 v64, v142
	v_mov_b32_e32 v65, v143
	v_mov_b32_e32 v66, v144
	v_mov_b32_e32 v67, v145
	v_mov_b32_e32 v68, v146
	v_mov_b32_e32 v69, v147
	s_nop 1
	v_mfma_f32_16x16x32_bf16 v[44:47], v[6:9], v[62:65], 0
	v_add_lshl_u32 v62, v42, s49, 2
	v_mov_b32_e32 v63, v27
	v_lshl_add_u64 v[42:43], v[12:13], 0, v[62:63]
	s_nop 0
	v_mfma_f32_16x16x32_bf16 v[14:17], v[6:9], v[14:17], 0
	v_mfma_f32_16x16x32_bf16 v[14:17], v[2:5], v[18:21], v[14:17]
	v_mfma_f32_16x16x32_bf16 v[18:21], v[2:5], v[66:69], v[44:47]
	s_nop 2
	v_lshl_add_u64 v[44:45], v[40:41], 0, v[62:63]
	v_lshl_add_u64 v[40:41], v[10:11], 0, v[62:63]
	s_nop 0
	s_nop 0
	s_waitcnt vmcnt(0) lgkmcnt(0)
	v_mov_b32_e32 v12, v180
	v_mov_b32_e32 v52, v181
	v_mov_b32_e32 v48, v182
	v_mul_f32_e64 v10, |v12|, s31
	v_exp_f32_e32 v50, v10
	v_max_f32_e64 v10, -v12, -v12
	v_max_f32_e32 v54, 0, v10
	v_add_f32_e32 v12, 1.0, v50
	v_add_f32_e32 v10, -1.0, v12
	v_sub_f32_e32 v11, v10, v12
	v_add_f32_e32 v11, 1.0, v11
	v_sub_f32_e32 v10, v50, v10
	v_add_f32_e32 v13, v10, v11
	v_frexp_mant_f32_e32 v29, v12
	v_cvt_f64_f32_e32 v[10:11], v12
	v_frexp_exp_i32_f64_e32 v10, v[10:11]
	v_cmp_gt_f32_e32 vcc, s33, v29
	v_add_f32_e32 v19, v19, v52
	v_mul_f32_e32 v19, 0xbfb8aa3b, v19
	v_subbrev_co_u32_e32 v64, vcc, 0, v10, vcc
	v_sub_u32_e32 v10, 0, v64
	v_ldexp_f32 v11, v12, v10
	v_add_f32_e32 v12, -1.0, v11
	v_add_f32_e32 v29, 1.0, v11
	v_ldexp_f32 v10, v13, v10
	v_add_f32_e32 v13, 1.0, v12
	v_add_f32_e32 v46, -1.0, v29
	v_sub_f32_e32 v13, v11, v13
	v_sub_f32_e32 v11, v11, v46
	v_add_f32_e32 v13, v10, v13
	v_add_f32_e32 v10, v10, v11
	v_add_f32_e32 v65, v29, v10
	v_rcp_f32_e32 v66, v65
	v_sub_f32_e32 v11, v65, v29
	v_sub_f32_e32 v29, v10, v11
	v_add_f32_e32 v11, v12, v13
	v_mul_f32_e32 v68, v11, v66
	v_sub_f32_e32 v10, v11, v12
	v_mul_f32_e32 v12, v65, v68
	v_fma_f32 v46, v68, v65, -v12
	v_fmac_f32_e32 v46, v68, v29
	v_sub_f32_e32 v67, v13, v10
	v_add_f32_e32 v10, v12, v46
	v_sub_f32_e32 v13, v11, v10
	v_pk_add_f32 v[62:63], v[10:11], v[12:13] neg_lo:[0,1] neg_hi:[0,1]
	v_mov_b32_e32 v47, v10
	v_pk_add_f32 v[10:11], v[62:63], v[46:47] neg_lo:[0,1] neg_hi:[0,1]
	v_cmp_neq_f32_e32 vcc, s35, v50
	v_add_f32_e32 v11, v67, v11
	v_add_f32_e32 v10, v10, v11
	v_add_f32_e32 v11, v13, v10
	v_mul_f32_e32 v67, v66, v11
	v_mul_f32_e32 v12, v65, v67
	v_fma_f32 v46, v67, v65, -v12
	v_fmac_f32_e32 v46, v67, v29
	v_sub_f32_e32 v13, v13, v11
	v_add_f32_e32 v29, v10, v13
	v_add_f32_e32 v10, v12, v46
	v_sub_f32_e32 v13, v11, v10
	v_pk_add_f32 v[62:63], v[10:11], v[12:13] neg_lo:[0,1] neg_hi:[0,1]
	v_mov_b32_e32 v47, v10
	v_pk_add_f32 v[10:11], v[62:63], v[46:47] neg_lo:[0,1] neg_hi:[0,1]
	v_exp_f32_e32 v19, v19
	v_add_f32_e32 v11, v29, v11
	v_add_f32_e32 v10, v10, v11
	v_add_f32_e32 v11, v68, v67
	v_add_f32_e32 v10, v13, v10
	v_sub_f32_e32 v12, v11, v68
	v_mul_f32_e32 v10, v66, v10
	v_sub_f32_e32 v12, v67, v12
	v_add_f32_e32 v12, v12, v10
	v_add_f32_e32 v46, v11, v12
	v_mul_f32_e32 v47, v46, v46
	v_fmamk_f32 v10, v47, 0x3e9b6dac, v1
	v_fmaak_f32 v29, v47, v10, 0x3f2aaada
	v_cvt_f32_i32_e32 v10, v64
	v_sub_f32_e32 v11, v46, v11
	v_sub_f32_e32 v11, v12, v11
	v_ldexp_f32 v62, v11, 1
	v_mul_f32_e32 v11, v46, v47
	v_ldexp_f32 v13, v46, 1
	v_pk_mul_f32 v[46:47], v[10:11], v[28:29]
	s_nop 0
	v_fma_f32 v12, v10, s34, -v46
	v_fmac_f32_e32 v12, 0xb102e308, v10
	v_pk_add_f32 v[10:11], v[46:47], v[12:13]
	s_nop 0
	v_sub_f32_e32 v13, v11, v13
	v_sub_f32_e32 v13, v47, v13
	v_add_f32_e32 v63, v62, v13
	v_mov_b32_e32 v62, v46
	v_pk_add_f32 v[46:47], v[10:11], v[46:47] neg_lo:[0,1] neg_hi:[0,1]
	v_pk_add_f32 v[64:65], v[10:11], v[62:63]
	v_mov_b32_e32 v13, v10
	v_mov_b32_e32 v47, v65
	v_pk_add_f32 v[66:67], v[12:13], v[46:47] neg_lo:[0,1] neg_hi:[0,1]
	v_pk_add_f32 v[12:13], v[12:13], v[46:47]
	v_mov_b32_e32 v62, v63
	v_pk_add_f32 v[46:47], v[12:13], v[10:11] op_sel:[1,0] op_sel_hi:[0,1] neg_lo:[0,1] neg_hi:[0,1]
	v_pk_add_f32 v[68:69], v[64:65], v[46:47] op_sel_hi:[1,0] neg_lo:[0,1] neg_hi:[0,1]
	v_mov_b32_e32 v64, v65
	v_mov_b32_e32 v65, v13
	v_pk_mov_b32 v[46:47], v[10:11], v[46:47] op_sel:[1,0]
	v_mov_b32_e32 v63, v10
	v_pk_add_f32 v[46:47], v[64:65], v[46:47] neg_lo:[0,1] neg_hi:[0,1]
	v_mov_b32_e32 v68, v66
	v_pk_add_f32 v[10:11], v[62:63], v[46:47] neg_lo:[0,1] neg_hi:[0,1]
	v_mov_b32_e32 v67, v13
	v_pk_add_f32 v[46:47], v[68:69], v[10:11]
	s_nop 0
	v_pk_add_f32 v[62:63], v[46:47], v[46:47] op_sel:[0,1] op_sel_hi:[1,0]
	s_nop 0
	v_pk_add_f32 v[12:13], v[12:13], v[62:63] op_sel:[1,0] op_sel_hi:[0,1]
	v_mov_b32_e32 v47, v12
	v_pk_add_f32 v[64:65], v[46:47], v[66:67] neg_lo:[0,1] neg_hi:[0,1]
	v_mov_b32_e32 v11, v62
	v_sub_f32_e32 v13, v46, v64
	v_pk_add_f32 v[10:11], v[10:11], v[64:65] neg_lo:[0,1] neg_hi:[0,1]
	v_sub_f32_e32 v13, v66, v13
	v_add_f32_e32 v10, v10, v13
	v_add_f32_e32 v10, v10, v11
	v_add_f32_e32 v11, v18, v52
	v_mul_f32_e32 v11, 0xbfb8aa3b, v11
	v_exp_f32_e32 v11, v11
	v_add_f32_e32 v10, v12, v10
	v_cndmask_b32_e32 v10, v58, v10, vcc
	v_cmp_ngt_f32_e32 vcc, -1.0, v50
	v_add_f32_e32 v11, 1.0, v11
	v_div_scale_f32 v12, s[0:1], v11, v11, 1.0
	v_rcp_f32_e32 v18, v12
	v_cndmask_b32_e32 v10, v59, v10, vcc
	v_cmp_neq_f32_e32 vcc, -1.0, v50
	v_add_f32_e32 v13, v14, v48
	v_fma_f32 v14, -v12, v18, 1.0
	v_cndmask_b32_e32 v10, v60, v10, vcc
	v_cmp_lt_f32_e64 vcc, |v50|, s36
	v_fmac_f32_e32 v18, v14, v18
	v_mul_f32_e32 v13, 0xbfb8aa3b, v13
	v_cndmask_b32_e32 v10, v10, v50, vcc
	v_div_scale_f32 v14, vcc, 1.0, v11, 1.0
	v_mul_f32_e32 v29, v14, v18
	v_fma_f32 v46, -v12, v29, v14
	v_fmac_f32_e32 v29, v46, v18
	v_fma_f32 v12, -v12, v29, v14
	v_div_fmas_f32 v14, v12, v18, v29
	v_add_f32_e32 v18, 1.0, v19
	v_div_scale_f32 v19, s[0:1], v18, v18, 1.0
	v_rcp_f32_e32 v29, v19
	v_add_f32_e32 v12, v15, v48
	v_mul_f32_e32 v12, 0xbfb8aa3b, v12
	v_exp_f32_e32 v13, v13
	v_exp_f32_e32 v12, v12
	v_fma_f32 v15, -v19, v29, 1.0
	v_fmac_f32_e32 v29, v15, v29
	v_div_scale_f32 v15, vcc, 1.0, v18, 1.0
	v_mul_f32_e32 v46, v15, v29
	v_fma_f32 v47, -v19, v46, v15
	v_pk_add_f32 v[12:13], v[12:13], 1.0 op_sel_hi:[1,0]
	v_fmac_f32_e32 v46, v47, v29
	v_div_scale_f32 v47, s[0:1], v13, v13, 1.0
	v_rcp_f32_e32 v50, v47
	v_fma_f32 v15, -v19, v46, v15
	v_div_fmas_f32 v15, v15, v29, v46
	v_add_f32_e32 v10, v54, v10
	v_fma_f32 v19, -v47, v50, 1.0
	v_fmac_f32_e32 v50, v19, v50
	v_div_scale_f32 v19, vcc, 1.0, v13, 1.0
	v_mul_f32_e32 v29, v19, v50
	v_fma_f32 v46, -v47, v29, v19
	v_fmac_f32_e32 v29, v46, v50
	v_div_scale_f32 v46, s[0:1], v12, v12, 1.0
	v_fma_f32 v19, -v47, v29, v19
	v_rcp_f32_e32 v47, v46
	v_div_fmas_f32 v19, v19, v50, v29
	v_div_fixup_f32 v13, v19, v13, 1.0
	v_mul_f32_e32 v10, 0xc1000000, v10
	v_fma_f32 v19, -v46, v47, 1.0
	v_fmac_f32_e32 v47, v19, v47
	v_div_scale_f32 v19, vcc, 1.0, v12, 1.0
	v_mul_f32_e32 v29, v19, v47
	v_fma_f32 v50, -v46, v29, v19
	v_fmac_f32_e32 v29, v50, v47
	v_fma_f32 v19, -v46, v29, v19
	v_div_fmas_f32 v19, v19, v47, v29
	v_div_fixup_f32 v12, v19, v12, 1.0
	v_pk_mul_f32 v[12:13], v[12:13], v[10:11] op_sel_hi:[1,0]
	v_div_fixup_f32 v11, v14, v11, 1.0
	v_mul_f32_e32 v19, 0x3fb8aa3b, v13
	v_fma_f32 v29, v13, s41, -v19
	v_rndne_f32_e32 v46, v19
	v_fmac_f32_e32 v29, 0x32a5705f, v13
	v_sub_f32_e32 v19, v19, v46
	v_add_f32_e32 v19, v19, v29
	v_exp_f32_e32 v19, v19
	v_cvt_i32_f32_e32 v29, v46
	v_cmp_ngt_f32_e32 vcc, s42, v13
	v_div_fixup_f32 v18, v15, v18, 1.0
	v_cmp_nlt_f32_e64 s[0:1], s43, v13
	v_ldexp_f32 v14, v19, v29
	v_cndmask_b32_e32 v19, 0, v14, vcc
	v_pk_add_f32 v[14:15], v[12:13], v[12:13]
	v_cndmask_b32_e64 v13, v58, v19, s[0:1]
	v_mul_f32_e32 v29, 0x3fb8aa3b, v15
	v_rndne_f32_e32 v29, v29
	v_fmamk_f32 v46, v29, 0xbf317218, v15
	v_fmac_f32_e32 v46, 0x3102e308, v29
	v_fmamk_f32 v47, v46, 0x395133b1, v56
	v_fmaak_f32 v47, v46, v47, 0x3c0887f9
	v_fmaak_f32 v47, v46, v47, 0x3d2aaa81
	v_cvt_i32_f32_e32 v50, v29
	v_fmaak_f32 v47, v46, v47, 0x3e2aaaab
	v_fma_f32 v47, v46, v47, 0.5
	v_mul_f32_e32 v47, v46, v47
	v_fmac_f32_e32 v46, v46, v47
	v_ldexp_f32 v47, 1.0, v50
	v_cmp_eq_f32_e32 vcc, s44, v29
	ds_write_b32 v35, v13 offset:25920
	s_nop 0
	v_cndmask_b32_e32 v29, v47, v61, vcc
	v_add_f32_e32 v47, -1.0, v29
	v_fmac_f32_e32 v47, v29, v46
	v_add_f32_e32 v29, v47, v47
	v_cndmask_b32_e32 v29, v47, v29, vcc
	v_cmp_nlt_f32_e32 vcc, s45, v15
	s_nop 1
	v_cndmask_b32_e64 v29, v60, -v29, vcc
	v_mul_f32_e32 v46, 0x4f800000, v29
	v_cmp_gt_f32_e32 vcc, s46, v29
	s_nop 1
	v_cndmask_b32_e32 v29, v29, v46, vcc
	v_sqrt_f32_e32 v46, v29
	s_nop 0
	v_add_u32_e32 v13, -1, v46
	v_fma_f32 v19, -v13, v46, v29
	v_cmp_ge_f32_e64 s[0:1], 0, v19
	v_add_u32_e32 v19, 1, v46
	s_nop 0
	v_cndmask_b32_e64 v13, v46, v13, s[0:1]
	v_fma_f32 v46, -v19, v46, v29
	v_cmp_lt_f32_e64 s[0:1], 0, v46
	s_nop 1
	v_cndmask_b32_e64 v13, v13, v19, s[0:1]
	v_mul_f32_e32 v19, 0x37800000, v13
	v_cndmask_b32_e32 v13, v13, v19, vcc
	v_cmp_class_f32_e32 vcc, v29, v57
	v_cmp_nlt_f32_e64 s[0:1], s43, v12
	s_nop 0
	v_cndmask_b32_e32 v13, v13, v29, vcc
	v_cmp_ngt_f32_e32 vcc, s47, v15
	v_mul_f32_e32 v15, 0x3fb8aa3b, v12
	v_fma_f32 v19, v12, s41, -v15
	v_rndne_f32_e32 v29, v15
	v_fmac_f32_e32 v19, 0x32a5705f, v12
	v_sub_f32_e32 v15, v15, v29
	v_add_f32_e32 v15, v15, v19
	v_exp_f32_e32 v15, v15
	v_cvt_i32_f32_e32 v19, v29
	v_cndmask_b32_e32 v13, 1.0, v13, vcc
	v_mul_f32_e32 v11, v11, v13
	v_mul_f32_e32 v13, 0x3fb8aa3b, v14
	v_mul_f32_e32 v11, v49, v11
	v_rndne_f32_e32 v13, v13
	ds_write_b32 v35, v11 offset:42560
	v_ldexp_f32 v11, v15, v19
	v_fmamk_f32 v15, v13, 0xbf317218, v14
	v_fmac_f32_e32 v15, 0x3102e308, v13
	v_fmamk_f32 v19, v15, 0x395133b1, v56
	v_fmaak_f32 v19, v15, v19, 0x3c0887f9
	v_fmaak_f32 v19, v15, v19, 0x3d2aaa81
	v_cvt_i32_f32_e32 v29, v13
	v_fmaak_f32 v19, v15, v19, 0x3e2aaaab
	v_fma_f32 v19, v15, v19, 0.5
	v_cmp_ngt_f32_e32 vcc, s42, v12
	v_mul_f32_e32 v19, v15, v19
	v_fmac_f32_e32 v15, v15, v19
	v_cndmask_b32_e32 v11, 0, v11, vcc
	v_ldexp_f32 v19, 1.0, v29
	v_cmp_eq_f32_e32 vcc, s44, v13
	v_cndmask_b32_e64 v11, v58, v11, s[0:1]
	ds_write_b32 v35, v11 offset:26180
	v_cndmask_b32_e32 v13, v19, v61, vcc
	v_add_f32_e32 v19, -1.0, v13
	v_fmac_f32_e32 v19, v13, v15
	v_add_f32_e32 v13, v19, v19
	v_cndmask_b32_e32 v13, v19, v13, vcc
	v_cmp_nlt_f32_e32 vcc, s45, v14
	s_nop 1
	v_cndmask_b32_e64 v13, v60, -v13, vcc
	v_mul_f32_e32 v15, 0x4f800000, v13
	v_cmp_gt_f32_e32 vcc, s46, v13
	s_nop 1
	v_cndmask_b32_e32 v13, v13, v15, vcc
	v_sqrt_f32_e32 v15, v13
	s_nop 0
	v_add_u32_e32 v11, -1, v15
	v_fma_f32 v12, -v11, v15, v13
	v_cmp_ge_f32_e64 s[0:1], 0, v12
	v_add_u32_e32 v12, 1, v15
	s_nop 0
	v_cndmask_b32_e64 v11, v15, v11, s[0:1]
	v_fma_f32 v15, -v12, v15, v13
	v_cmp_lt_f32_e64 s[0:1], 0, v15
	s_nop 1
	v_cndmask_b32_e64 v11, v11, v12, s[0:1]
	v_mul_f32_e32 v12, 0x37800000, v11
	v_cndmask_b32_e32 v11, v11, v12, vcc
	v_add_f32_e32 v12, v20, v52
	v_mul_f32_e32 v12, 0xbfb8aa3b, v12
	v_exp_f32_e32 v12, v12
	v_cmp_class_f32_e32 vcc, v13, v57
	v_add_f32_e32 v15, 1.0, v12
	s_nop 0
	v_cndmask_b32_e32 v11, v11, v13, vcc
	v_cmp_ngt_f32_e32 vcc, s47, v14
	v_add_f32_e32 v13, v16, v48
	v_mul_f32_e32 v13, 0xbfb8aa3b, v13
	v_cndmask_b32_e32 v11, 1.0, v11, vcc
	v_mul_f32_e32 v11, v18, v11
	v_mul_f32_e32 v14, v53, v11
	v_div_scale_f32 v11, s[0:1], v15, v15, 1.0
	v_rcp_f32_e32 v12, v11
	v_exp_f32_e32 v13, v13
	ds_write_b32 v35, v14 offset:42820
	v_fma_f32 v16, -v11, v12, 1.0
	v_fmac_f32_e32 v12, v16, v12
	v_div_scale_f32 v16, vcc, 1.0, v15, 1.0
	v_mul_f32_e32 v18, v16, v12
	v_fma_f32 v19, -v11, v18, v16
	v_fmac_f32_e32 v18, v19, v12
	v_add_f32_e32 v19, v21, v52
	v_mul_f32_e32 v19, 0xbfb8aa3b, v19
	v_exp_f32_e32 v19, v19
	v_fma_f32 v11, -v11, v18, v16
	v_div_fmas_f32 v16, v11, v12, v18
	v_add_f32_e32 v12, v17, v48
	v_add_f32_e32 v18, 1.0, v19
	v_div_scale_f32 v11, s[0:1], v18, v18, 1.0
	v_rcp_f32_e32 v19, v11
	v_mul_f32_e32 v12, 0xbfb8aa3b, v12
	v_exp_f32_e32 v12, v12
	v_div_fixup_f32 v14, v16, v15, 1.0
	v_fma_f32 v17, -v11, v19, 1.0
	v_fmac_f32_e32 v19, v17, v19
	v_div_scale_f32 v17, vcc, 1.0, v18, 1.0
	v_mul_f32_e32 v20, v17, v19
	v_fma_f32 v21, -v11, v20, v17
	v_pk_add_f32 v[12:13], v[12:13], 1.0 op_sel_hi:[1,0]
	v_fmac_f32_e32 v20, v21, v19
	v_div_scale_f32 v21, s[0:1], v13, v13, 1.0
	v_rcp_f32_e32 v29, v21
	v_fma_f32 v11, -v11, v20, v17
	v_div_fmas_f32 v17, v11, v19, v20
	v_div_fixup_f32 v15, v17, v18, 1.0
	v_fma_f32 v11, -v21, v29, 1.0
	v_fmac_f32_e32 v29, v11, v29
	v_div_scale_f32 v11, vcc, 1.0, v13, 1.0
	v_mul_f32_e32 v19, v11, v29
	v_fma_f32 v20, -v21, v19, v11
	v_fmac_f32_e32 v19, v20, v29
	v_div_scale_f32 v20, s[0:1], v12, v12, 1.0
	v_fma_f32 v11, -v21, v19, v11
	v_rcp_f32_e32 v21, v20
	v_div_fmas_f32 v11, v11, v29, v19
	v_div_fixup_f32 v13, v11, v13, 1.0
	v_fma_f32 v11, -v20, v21, 1.0
	v_fmac_f32_e32 v21, v11, v21
	v_div_scale_f32 v11, vcc, 1.0, v12, 1.0
	v_mul_f32_e32 v19, v11, v21
	v_fma_f32 v29, -v20, v19, v11
	v_fmac_f32_e32 v19, v29, v21
	v_fma_f32 v11, -v20, v19, v11
	v_div_fmas_f32 v11, v11, v21, v19
	v_div_fixup_f32 v12, v11, v12, 1.0
	v_pk_mul_f32 v[10:11], v[12:13], v[10:11] op_sel_hi:[1,0]
	s_nop 0
	v_mul_f32_e32 v12, 0x3fb8aa3b, v11
	v_fma_f32 v13, v11, s41, -v12
	v_rndne_f32_e32 v19, v12
	v_fmac_f32_e32 v13, 0x32a5705f, v11
	v_sub_f32_e32 v12, v12, v19
	v_add_f32_e32 v12, v12, v13
	v_exp_f32_e32 v12, v12
	v_cvt_i32_f32_e32 v13, v19
	v_cmp_ngt_f32_e32 vcc, s42, v11
	v_cmp_nlt_f32_e64 s[0:1], s43, v11
	v_ldexp_f32 v12, v12, v13
	v_cndmask_b32_e32 v16, 0, v12, vcc
	v_pk_add_f32 v[12:13], v[10:11], v[10:11]
	v_cndmask_b32_e64 v11, v58, v16, s[0:1]
	v_mul_f32_e32 v17, 0x3fb8aa3b, v13
	v_rndne_f32_e32 v17, v17
	v_fmamk_f32 v18, v17, 0xbf317218, v13
	v_fmac_f32_e32 v18, 0x3102e308, v17
	v_fmamk_f32 v19, v18, 0x395133b1, v56
	v_fmaak_f32 v19, v18, v19, 0x3c0887f9
	v_fmaak_f32 v19, v18, v19, 0x3d2aaa81
	v_cvt_i32_f32_e32 v20, v17
	v_fmaak_f32 v19, v18, v19, 0x3e2aaaab
	v_fma_f32 v19, v18, v19, 0.5
	v_mul_f32_e32 v19, v18, v19
	v_fmac_f32_e32 v18, v18, v19
	v_ldexp_f32 v19, 1.0, v20
	v_cmp_eq_f32_e32 vcc, s44, v17
	ds_write_b32 v35, v11 offset:26440
	s_nop 0
	v_cndmask_b32_e32 v17, v19, v61, vcc
	v_add_f32_e32 v19, -1.0, v17
	v_fmac_f32_e32 v19, v17, v18
	v_add_f32_e32 v17, v19, v19
	v_cndmask_b32_e32 v17, v19, v17, vcc
	v_cmp_nlt_f32_e32 vcc, s45, v13
	s_nop 1
	v_cndmask_b32_e64 v17, v60, -v17, vcc
	v_mul_f32_e32 v18, 0x4f800000, v17
	v_cmp_gt_f32_e32 vcc, s46, v17
	s_nop 1
	v_cndmask_b32_e32 v17, v17, v18, vcc
	v_sqrt_f32_e32 v18, v17
	s_nop 0
	v_add_u32_e32 v11, -1, v18
	v_fma_f32 v16, -v11, v18, v17
	v_cmp_ge_f32_e64 s[0:1], 0, v16
	v_add_u32_e32 v16, 1, v18
	s_nop 0
	v_cndmask_b32_e64 v11, v18, v11, s[0:1]
	v_fma_f32 v18, -v16, v18, v17
	v_cmp_lt_f32_e64 s[0:1], 0, v18
	s_nop 1
	v_cndmask_b32_e64 v11, v11, v16, s[0:1]
	v_mul_f32_e32 v16, 0x37800000, v11
	v_cndmask_b32_e32 v11, v11, v16, vcc
	v_cmp_class_f32_e32 vcc, v17, v57
	v_cmp_nlt_f32_e64 s[0:1], s43, v10
	s_nop 0
	v_cndmask_b32_e32 v11, v11, v17, vcc
	v_cmp_ngt_f32_e32 vcc, s47, v13
	v_mul_f32_e32 v13, 0x3fb8aa3b, v10
	v_fma_f32 v16, v10, s41, -v13
	v_rndne_f32_e32 v17, v13
	v_fmac_f32_e32 v16, 0x32a5705f, v10
	v_sub_f32_e32 v13, v13, v17
	v_add_f32_e32 v13, v13, v16
	v_exp_f32_e32 v13, v13
	v_cvt_i32_f32_e32 v16, v17
	v_cndmask_b32_e32 v11, 1.0, v11, vcc
	v_mul_f32_e32 v11, v14, v11
	v_mul_f32_e32 v11, v51, v11
	ds_write_b32 v35, v11 offset:43080
	v_ldexp_f32 v11, v13, v16
	v_mul_f32_e32 v13, 0x3fb8aa3b, v12
	v_rndne_f32_e32 v13, v13
	v_fmamk_f32 v14, v13, 0xbf317218, v12
	v_fmac_f32_e32 v14, 0x3102e308, v13
	v_fmamk_f32 v16, v14, 0x395133b1, v56
	v_fmaak_f32 v16, v14, v16, 0x3c0887f9
	v_fmaak_f32 v16, v14, v16, 0x3d2aaa81
	v_cvt_i32_f32_e32 v17, v13
	v_fmaak_f32 v16, v14, v16, 0x3e2aaaab
	v_fma_f32 v16, v14, v16, 0.5
	v_cmp_ngt_f32_e32 vcc, s42, v10
	v_mul_f32_e32 v16, v14, v16
	v_fmac_f32_e32 v14, v14, v16
	v_cndmask_b32_e32 v11, 0, v11, vcc
	v_ldexp_f32 v16, 1.0, v17
	v_cmp_eq_f32_e32 vcc, s44, v13
	v_cndmask_b32_e64 v10, v58, v11, s[0:1]
	ds_write_b32 v35, v10 offset:26700
	v_cndmask_b32_e32 v13, v16, v61, vcc
	v_add_f32_e32 v16, -1.0, v13
	v_fmac_f32_e32 v16, v13, v14
	v_add_f32_e32 v13, v16, v16
	v_cndmask_b32_e32 v13, v16, v13, vcc
	v_cmp_nlt_f32_e32 vcc, s45, v12
	s_nop 1
	v_cndmask_b32_e64 v13, v60, -v13, vcc
	v_mul_f32_e32 v14, 0x4f800000, v13
	v_cmp_gt_f32_e32 vcc, s46, v13
	s_nop 1
	v_cndmask_b32_e32 v13, v13, v14, vcc
	v_sqrt_f32_e32 v14, v13
	s_nop 0
	v_add_u32_e32 v10, -1, v14
	v_fma_f32 v11, -v10, v14, v13
	v_cmp_ge_f32_e64 s[0:1], 0, v11
	v_add_u32_e32 v11, 1, v14
	s_nop 0
	v_cndmask_b32_e64 v10, v14, v10, s[0:1]
	v_fma_f32 v14, -v11, v14, v13
	v_cmp_lt_f32_e64 s[0:1], 0, v14
	v_or_b32_e32 v14, 0x1000, v26
	v_or_b32_e32 v26, 0x1800, v26
	v_cndmask_b32_e64 v10, v10, v11, s[0:1]
	v_mul_f32_e32 v11, 0x37800000, v10
	v_cndmask_b32_e32 v10, v10, v11, vcc
	v_cmp_class_f32_e32 vcc, v13, v57
	s_nop 1
	v_cndmask_b32_e32 v10, v10, v13, vcc
	v_cmp_ngt_f32_e32 vcc, s47, v12
	s_nop 1
	v_cndmask_b32_e32 v10, 1.0, v10, vcc
	v_mul_f32_e32 v10, v15, v10
	v_mul_f32_e32 v10, v55, v10
	v_mov_b32_e32 v15, v27
	ds_write_b32 v35, v10 offset:43340
	v_lshl_add_u64 v[16:17], v[36:37], 0, v[14:15]
	s_nop 0
	v_lshl_add_u64 v[50:51], v[38:39], 0, v[14:15]
	s_nop 0
	s_nop 0
	s_nop 0
	s_nop 0
	s_nop 0
	s_nop 0
	s_waitcnt vmcnt(0) lgkmcnt(0)
	v_mov_b32_e32 v10, v148
	v_mov_b32_e32 v11, v149
	v_mov_b32_e32 v12, v150
	v_mov_b32_e32 v13, v151
	v_mov_b32_e32 v14, v152
	v_mov_b32_e32 v15, v153
	v_mov_b32_e32 v16, v154
	v_mov_b32_e32 v17, v155
	v_mov_b32_e32 v18, v156
	v_mov_b32_e32 v19, v157
	v_mov_b32_e32 v20, v158
	v_mov_b32_e32 v21, v159
	v_mov_b32_e32 v46, v160
	v_mov_b32_e32 v47, v161
	v_mov_b32_e32 v48, v162
	v_mov_b32_e32 v49, v163
	v_mov_b32_e32 v29, v183
	v_mov_b32_e32 v64, v184
	s_nop 1
	v_mfma_f32_16x16x32_bf16 v[10:13], v[6:9], v[10:13], 0
	s_nop 0
	v_lshl_add_u64 v[36:37], v[36:37], 0, v[26:27]
	v_mfma_f32_16x16x32_bf16 v[18:21], v[6:9], v[18:21], 0
	v_mfma_f32_16x16x32_bf16 v[10:13], v[2:5], v[14:17], v[10:13]
	v_mfma_f32_16x16x32_bf16 v[14:17], v[2:5], v[46:49], v[18:21]
	s_nop 5
	v_mul_f32_e64 v18, |v29|, s31
	v_exp_f32_e32 v63, v18
	v_max_f32_e64 v18, -v29, -v29
	v_max_f32_e32 v65, 0, v18
	v_add_f32_e32 v14, v14, v64
	v_add_f32_e32 v20, 1.0, v63
	v_add_f32_e32 v18, -1.0, v20
	v_sub_f32_e32 v19, v18, v20
	v_add_f32_e32 v19, 1.0, v19
	v_sub_f32_e32 v18, v63, v18
	v_add_f32_e32 v21, v18, v19
	v_frexp_mant_f32_e32 v29, v20
	v_cvt_f64_f32_e32 v[18:19], v20
	v_frexp_exp_i32_f64_e32 v18, v[18:19]
	v_cmp_gt_f32_e32 vcc, s33, v29
	v_mul_f32_e32 v14, 0xbfb8aa3b, v14
	v_exp_f32_e32 v14, v14
	v_subbrev_co_u32_e32 v50, vcc, 0, v18, vcc
	v_sub_u32_e32 v18, 0, v50
	v_ldexp_f32 v19, v20, v18
	v_add_f32_e32 v20, -1.0, v19
	v_add_f32_e32 v29, 1.0, v19
	v_ldexp_f32 v18, v21, v18
	v_add_f32_e32 v21, 1.0, v20
	v_add_f32_e32 v46, -1.0, v29
	v_sub_f32_e32 v21, v19, v21
	v_sub_f32_e32 v19, v19, v46
	v_add_f32_e32 v21, v18, v21
	v_add_f32_e32 v18, v18, v19
	v_add_f32_e32 v51, v29, v18
	v_rcp_f32_e32 v52, v51
	v_sub_f32_e32 v19, v51, v29
	v_sub_f32_e32 v29, v18, v19
	v_add_f32_e32 v19, v20, v21
	v_mul_f32_e32 v54, v19, v52
	v_sub_f32_e32 v18, v19, v20
	v_mul_f32_e32 v20, v51, v54
	v_fma_f32 v46, v54, v51, -v20
	v_fmac_f32_e32 v46, v54, v29
	v_sub_f32_e32 v53, v21, v18
	v_add_f32_e32 v18, v20, v46
	v_sub_f32_e32 v21, v19, v18
	v_pk_add_f32 v[48:49], v[18:19], v[20:21] neg_lo:[0,1] neg_hi:[0,1]
	v_mov_b32_e32 v47, v18
	v_pk_add_f32 v[18:19], v[48:49], v[46:47] neg_lo:[0,1] neg_hi:[0,1]
	v_cmp_neq_f32_e32 vcc, s35, v63
	v_add_f32_e32 v19, v53, v19
	v_add_f32_e32 v18, v18, v19
	v_add_f32_e32 v19, v21, v18
	v_mul_f32_e32 v53, v52, v19
	v_mul_f32_e32 v20, v51, v53
	v_fma_f32 v46, v53, v51, -v20
	v_fmac_f32_e32 v46, v53, v29
	v_sub_f32_e32 v21, v21, v19
	v_add_f32_e32 v29, v18, v21
	v_add_f32_e32 v18, v20, v46
	v_sub_f32_e32 v21, v19, v18
	v_pk_add_f32 v[48:49], v[18:19], v[20:21] neg_lo:[0,1] neg_hi:[0,1]
	v_mov_b32_e32 v47, v18
	v_pk_add_f32 v[18:19], v[48:49], v[46:47] neg_lo:[0,1] neg_hi:[0,1]
	v_add_f32_e32 v15, v15, v64
	v_add_f32_e32 v19, v29, v19
	v_add_f32_e32 v18, v18, v19
	v_add_f32_e32 v19, v54, v53
	v_add_f32_e32 v18, v21, v18
	v_sub_f32_e32 v20, v19, v54
	v_mul_f32_e32 v18, v52, v18
	v_sub_f32_e32 v20, v53, v20
	v_add_f32_e32 v20, v20, v18
	v_add_f32_e32 v46, v19, v20
	v_mul_f32_e32 v47, v46, v46
	v_fmamk_f32 v18, v47, 0x3e9b6dac, v1
	v_fmaak_f32 v29, v47, v18, 0x3f2aaada
	v_cvt_f32_i32_e32 v18, v50
	v_sub_f32_e32 v19, v46, v19
	v_sub_f32_e32 v19, v20, v19
	v_ldexp_f32 v48, v19, 1
	v_mul_f32_e32 v19, v46, v47
	v_ldexp_f32 v21, v46, 1
	v_pk_mul_f32 v[46:47], v[18:19], v[28:29]
	s_waitcnt vmcnt(0) lgkmcnt(0)
	v_mov_b32_e32 v62, v185
	v_add_f32_e32 v10, v10, v62
	v_fma_f32 v20, v18, s34, -v46
	v_fmac_f32_e32 v20, 0xb102e308, v18
	v_pk_add_f32 v[18:19], v[46:47], v[20:21]
	v_mul_f32_e32 v10, 0xbfb8aa3b, v10
	v_sub_f32_e32 v21, v19, v21
	v_sub_f32_e32 v21, v47, v21
	v_add_f32_e32 v49, v48, v21
	v_mov_b32_e32 v48, v46
	v_pk_add_f32 v[46:47], v[18:19], v[46:47] neg_lo:[0,1] neg_hi:[0,1]
	v_pk_add_f32 v[50:51], v[18:19], v[48:49]
	v_mov_b32_e32 v21, v18
	v_mov_b32_e32 v47, v51
	v_pk_add_f32 v[52:53], v[20:21], v[46:47] neg_lo:[0,1] neg_hi:[0,1]
	v_pk_add_f32 v[20:21], v[20:21], v[46:47]
	v_mov_b32_e32 v48, v49
	v_pk_add_f32 v[46:47], v[20:21], v[18:19] op_sel:[1,0] op_sel_hi:[0,1] neg_lo:[0,1] neg_hi:[0,1]
	v_pk_add_f32 v[54:55], v[50:51], v[46:47] op_sel_hi:[1,0] neg_lo:[0,1] neg_hi:[0,1]
	v_mov_b32_e32 v50, v51
	v_mov_b32_e32 v51, v21
	v_pk_mov_b32 v[46:47], v[18:19], v[46:47] op_sel:[1,0]
	v_mov_b32_e32 v49, v18
	v_pk_add_f32 v[46:47], v[50:51], v[46:47] neg_lo:[0,1] neg_hi:[0,1]
	v_mov_b32_e32 v54, v52
	v_pk_add_f32 v[18:19], v[48:49], v[46:47] neg_lo:[0,1] neg_hi:[0,1]
	v_mov_b32_e32 v53, v21
	v_pk_add_f32 v[46:47], v[54:55], v[18:19]
	v_mul_f32_e32 v15, 0xbfb8aa3b, v15
	v_pk_add_f32 v[48:49], v[46:47], v[46:47] op_sel:[0,1] op_sel_hi:[1,0]
	v_exp_f32_e32 v15, v15
	v_pk_add_f32 v[20:21], v[20:21], v[48:49] op_sel:[1,0] op_sel_hi:[0,1]
	v_mov_b32_e32 v47, v20
	v_pk_add_f32 v[50:51], v[46:47], v[52:53] neg_lo:[0,1] neg_hi:[0,1]
	v_mov_b32_e32 v19, v48
	v_sub_f32_e32 v21, v46, v50
	v_pk_add_f32 v[18:19], v[18:19], v[50:51] neg_lo:[0,1] neg_hi:[0,1]
	v_sub_f32_e32 v21, v52, v21
	v_add_f32_e32 v18, v18, v21
	v_add_f32_e32 v18, v18, v19
	v_add_f32_e32 v19, 1.0, v14
	v_div_scale_f32 v14, s[0:1], v19, v19, 1.0
	v_add_f32_e32 v18, v20, v18
	v_rcp_f32_e32 v20, v14
	v_cndmask_b32_e32 v18, v58, v18, vcc
	v_cmp_ngt_f32_e32 vcc, -1.0, v63
	v_exp_f32_e32 v21, v10
	v_fma_f32 v10, -v14, v20, 1.0
	v_cndmask_b32_e32 v18, v59, v18, vcc
	v_cmp_neq_f32_e32 vcc, -1.0, v63
	v_fmac_f32_e32 v20, v10, v20
	v_add_f32_e32 v16, v16, v64
	v_cndmask_b32_e32 v18, v60, v18, vcc
	v_cmp_lt_f32_e64 vcc, |v63|, s36
	v_mul_f32_e32 v16, 0xbfb8aa3b, v16
	v_exp_f32_e32 v16, v16
	v_cndmask_b32_e32 v18, v18, v63, vcc
	v_div_scale_f32 v10, vcc, 1.0, v19, 1.0
	v_mul_f32_e32 v29, v10, v20
	v_fma_f32 v46, -v14, v29, v10
	v_fmac_f32_e32 v29, v46, v20
	v_add_f32_e32 v46, 1.0, v15
	v_fma_f32 v10, -v14, v29, v10
	v_div_scale_f32 v14, s[0:1], v46, v46, 1.0
	v_rcp_f32_e32 v15, v14
	v_div_fmas_f32 v29, v10, v20, v29
	v_add_f32_e32 v10, v11, v62
	v_mul_f32_e32 v10, 0xbfb8aa3b, v10
	v_exp_f32_e32 v20, v10
	v_fma_f32 v10, -v14, v15, 1.0
	v_fmac_f32_e32 v15, v10, v15
	v_div_scale_f32 v47, vcc, 1.0, v46, 1.0
	v_mul_f32_e32 v48, v47, v15
	v_fma_f32 v10, -v14, v48, v47
	v_fmac_f32_e32 v48, v10, v15
	v_pk_add_f32 v[10:11], v[20:21], 1.0 op_sel_hi:[1,0]
	v_fma_f32 v14, -v14, v48, v47
	v_div_scale_f32 v20, s[0:1], v11, v11, 1.0
	v_rcp_f32_e32 v21, v20
	v_div_fmas_f32 v47, v14, v15, v48
	v_add_f32_e32 v18, v65, v18
	v_mul_f32_e32 v18, 0xc1000000, v18
	v_fma_f32 v14, -v20, v21, 1.0
	v_fmac_f32_e32 v21, v14, v21
	v_div_scale_f32 v14, vcc, 1.0, v11, 1.0
	v_mul_f32_e32 v15, v14, v21
	v_fma_f32 v48, -v20, v15, v14
	v_fmac_f32_e32 v15, v48, v21
	v_fma_f32 v14, -v20, v15, v14
	v_div_scale_f32 v20, s[0:1], v10, v10, 1.0
	v_rcp_f32_e32 v48, v20
	v_div_fmas_f32 v14, v14, v21, v15
	v_div_fixup_f32 v11, v14, v11, 1.0
	v_add_f32_e32 v12, v12, v62
	v_fma_f32 v14, -v20, v48, 1.0
	v_fmac_f32_e32 v48, v14, v48
	v_div_scale_f32 v14, vcc, 1.0, v10, 1.0
	v_mul_f32_e32 v15, v14, v48
	v_fma_f32 v21, -v20, v15, v14
	v_fmac_f32_e32 v15, v21, v48
	v_fma_f32 v14, -v20, v15, v14
	v_div_fmas_f32 v14, v14, v48, v15
	v_div_fixup_f32 v10, v14, v10, 1.0
	v_pk_mul_f32 v[14:15], v[10:11], v[18:19] op_sel_hi:[1,0]
	v_div_fixup_f32 v19, v29, v19, 1.0
	v_mul_f32_e32 v10, 0x3fb8aa3b, v15
	v_fma_f32 v11, v15, s41, -v10
	v_rndne_f32_e32 v20, v10
	v_fmac_f32_e32 v11, 0x32a5705f, v15
	v_sub_f32_e32 v10, v10, v20
	v_add_f32_e32 v10, v10, v11
	v_exp_f32_e32 v21, v10
	v_cvt_i32_f32_e32 v20, v20
	v_cmp_ngt_f32_e32 vcc, s42, v15
	v_div_fixup_f32 v29, v47, v46, 1.0
	v_cmp_nlt_f32_e64 s[0:1], s43, v15
	v_ldexp_f32 v20, v21, v20
	v_cndmask_b32_e32 v46, 0, v20, vcc
	v_pk_add_f32 v[20:21], v[14:15], v[14:15]
	v_cndmask_b32_e64 v15, v58, v46, s[0:1]
	v_mul_f32_e32 v47, 0x3fb8aa3b, v21
	v_rndne_f32_e32 v47, v47
	v_fmamk_f32 v48, v47, 0xbf317218, v21
	v_fmac_f32_e32 v48, 0x3102e308, v47
	v_fmamk_f32 v49, v48, 0x395133b1, v56
	v_fmaak_f32 v49, v48, v49, 0x3c0887f9
	v_fmaak_f32 v49, v48, v49, 0x3d2aaa81
	v_cvt_i32_f32_e32 v50, v47
	v_fmaak_f32 v49, v48, v49, 0x3e2aaaab
	v_fma_f32 v49, v48, v49, 0.5
	v_mul_f32_e32 v49, v48, v49
	v_fmac_f32_e32 v48, v48, v49
	v_ldexp_f32 v49, 1.0, v50
	v_cmp_eq_f32_e32 vcc, s44, v47
	ds_write_b32 v35, v15 offset:25984
	ds_read2_b32 v[10:11], v35 offset0:32 offset1:48
	v_cndmask_b32_e32 v47, v49, v61, vcc
	v_add_f32_e32 v49, -1.0, v47
	v_fmac_f32_e32 v49, v47, v48
	v_add_f32_e32 v47, v49, v49
	v_cndmask_b32_e32 v47, v49, v47, vcc
	v_cmp_nlt_f32_e32 vcc, s45, v21
	v_mul_f32_e32 v12, 0xbfb8aa3b, v12
	v_add_f32_e32 v17, v17, v64
	v_cndmask_b32_e64 v47, v60, -v47, vcc
	v_mul_f32_e32 v48, 0x4f800000, v47
	v_cmp_gt_f32_e32 vcc, s46, v47
	v_mul_f32_e32 v17, 0xbfb8aa3b, v17
	v_exp_f32_e32 v17, v17
	v_cndmask_b32_e32 v47, v47, v48, vcc
	v_sqrt_f32_e32 v48, v47
	v_lshl_add_u64 v[54:55], v[38:39], 0, v[26:27]
	v_add_u32_e32 v15, -1, v48
	v_fma_f32 v46, -v15, v48, v47
	v_cmp_ge_f32_e64 s[0:1], 0, v46
	v_add_u32_e32 v46, 1, v48
	s_nop 0
	v_cndmask_b32_e64 v15, v48, v15, s[0:1]
	v_fma_f32 v48, -v46, v48, v47
	v_cmp_lt_f32_e64 s[0:1], 0, v48
	s_nop 1
	v_cndmask_b32_e64 v15, v15, v46, s[0:1]
	v_mul_f32_e32 v46, 0x37800000, v15
	v_cndmask_b32_e32 v15, v15, v46, vcc
	v_cmp_class_f32_e32 vcc, v47, v57
	v_cmp_nlt_f32_e64 s[0:1], s43, v14
	s_nop 0
	v_cndmask_b32_e32 v15, v15, v47, vcc
	v_cmp_ngt_f32_e32 vcc, s47, v21
	v_mul_f32_e32 v21, 0x3fb8aa3b, v14
	v_fma_f32 v46, v14, s41, -v21
	v_rndne_f32_e32 v47, v21
	v_cndmask_b32_e32 v15, 1.0, v15, vcc
	v_fmac_f32_e32 v46, 0x32a5705f, v14
	v_sub_f32_e32 v21, v21, v47
	v_add_f32_e32 v21, v21, v46
	v_mul_f32_e32 v15, v19, v15
	v_exp_f32_e32 v21, v21
	v_cvt_i32_f32_e32 v46, v47
	s_waitcnt lgkmcnt(0)
	v_mul_f32_e32 v10, v10, v15
	v_mul_f32_e32 v15, 0x3fb8aa3b, v20
	v_rndne_f32_e32 v15, v15
	v_fmamk_f32 v19, v15, 0xbf317218, v20
	v_fmac_f32_e32 v19, 0x3102e308, v15
	ds_write_b32 v35, v10 offset:42624
	v_ldexp_f32 v10, v21, v46
	v_fmamk_f32 v21, v19, 0x395133b1, v56
	v_fmaak_f32 v21, v19, v21, 0x3c0887f9
	v_fmaak_f32 v21, v19, v21, 0x3d2aaa81
	v_cvt_i32_f32_e32 v46, v15
	v_fmaak_f32 v21, v19, v21, 0x3e2aaaab
	v_fma_f32 v21, v19, v21, 0.5
	v_cmp_ngt_f32_e32 vcc, s42, v14
	v_mul_f32_e32 v21, v19, v21
	v_fmac_f32_e32 v19, v19, v21
	v_cndmask_b32_e32 v10, 0, v10, vcc
	v_ldexp_f32 v21, 1.0, v46
	v_cmp_eq_f32_e32 vcc, s44, v15
	v_cndmask_b32_e64 v10, v58, v10, s[0:1]
	ds_write_b32 v35, v10 offset:26244
	v_cndmask_b32_e32 v15, v21, v61, vcc
	v_add_f32_e32 v21, -1.0, v15
	v_fmac_f32_e32 v21, v15, v19
	v_add_f32_e32 v15, v21, v21
	v_cndmask_b32_e32 v15, v21, v15, vcc
	v_cmp_nlt_f32_e32 vcc, s45, v20
	v_exp_f32_e32 v21, v12
	s_nop 0
	v_cndmask_b32_e64 v15, v60, -v15, vcc
	v_mul_f32_e32 v19, 0x4f800000, v15
	v_cmp_gt_f32_e32 vcc, s46, v15
	s_nop 1
	v_cndmask_b32_e32 v15, v15, v19, vcc
	v_sqrt_f32_e32 v19, v15
	s_nop 0
	v_add_u32_e32 v10, -1, v19
	v_fma_f32 v14, -v10, v19, v15
	v_cmp_ge_f32_e64 s[0:1], 0, v14
	v_add_u32_e32 v14, 1, v19
	s_nop 0
	v_cndmask_b32_e64 v10, v19, v10, s[0:1]
	v_fma_f32 v19, -v14, v19, v15
	v_cmp_lt_f32_e64 s[0:1], 0, v19
	s_nop 1
	v_cndmask_b32_e64 v10, v10, v14, s[0:1]
	v_mul_f32_e32 v14, 0x37800000, v10
	v_cndmask_b32_e32 v10, v10, v14, vcc
	v_cmp_class_f32_e32 vcc, v15, v57
	s_nop 1
	v_cndmask_b32_e32 v10, v10, v15, vcc
	ds_read2_b32 v[14:15], v35 offset0:97 offset1:113
	v_cmp_ngt_f32_e32 vcc, s47, v20
	s_nop 1
	v_cndmask_b32_e32 v10, 1.0, v10, vcc
	v_mul_f32_e32 v10, v29, v10
	s_waitcnt lgkmcnt(0)
	v_mul_f32_e32 v10, v14, v10
	ds_write_b32 v35, v10 offset:42884
	v_add_f32_e32 v10, 1.0, v16
	v_div_scale_f32 v14, s[0:1], v10, v10, 1.0
	v_rcp_f32_e32 v16, v14
	s_nop 0
	v_fma_f32 v12, -v14, v16, 1.0
	v_fmac_f32_e32 v16, v12, v16
	v_div_scale_f32 v12, vcc, 1.0, v10, 1.0
	v_mul_f32_e32 v19, v12, v16
	v_fma_f32 v20, -v14, v19, v12
	v_fmac_f32_e32 v19, v20, v16
	v_fma_f32 v12, -v14, v19, v12
	v_div_fmas_f32 v14, v12, v16, v19
	v_add_f32_e32 v19, 1.0, v17
	v_div_scale_f32 v16, s[0:1], v19, v19, 1.0
	v_rcp_f32_e32 v17, v16
	v_add_f32_e32 v12, v13, v62
	v_mul_f32_e32 v12, 0xbfb8aa3b, v12
	v_exp_f32_e32 v20, v12
	v_fma_f32 v12, -v16, v17, 1.0
	v_fmac_f32_e32 v17, v12, v17
	v_div_scale_f32 v29, vcc, 1.0, v19, 1.0
	v_mul_f32_e32 v46, v29, v17
	v_fma_f32 v12, -v16, v46, v29
	v_fmac_f32_e32 v46, v12, v17
	v_pk_add_f32 v[12:13], v[20:21], 1.0 op_sel_hi:[1,0]
	v_fma_f32 v16, -v16, v46, v29
	v_div_scale_f32 v20, s[0:1], v13, v13, 1.0
	v_rcp_f32_e32 v21, v20
	v_div_fmas_f32 v29, v16, v17, v46
	v_div_fixup_f32 v10, v14, v10, 1.0
	v_div_fixup_f32 v14, v29, v19, 1.0
	v_fma_f32 v16, -v20, v21, 1.0
	v_fmac_f32_e32 v21, v16, v21
	v_div_scale_f32 v16, vcc, 1.0, v13, 1.0
	v_mul_f32_e32 v17, v16, v21
	v_fma_f32 v46, -v20, v17, v16
	v_fmac_f32_e32 v17, v46, v21
	v_fma_f32 v16, -v20, v17, v16
	v_div_scale_f32 v20, s[0:1], v12, v12, 1.0
	v_rcp_f32_e32 v46, v20
	v_div_fmas_f32 v16, v16, v21, v17
	v_div_fixup_f32 v13, v16, v13, 1.0
	v_fma_f32 v16, -v20, v46, 1.0
	v_fmac_f32_e32 v46, v16, v46
	v_div_scale_f32 v16, vcc, 1.0, v12, 1.0
	v_mul_f32_e32 v17, v16, v46
	v_fma_f32 v21, -v20, v17, v16
	v_fmac_f32_e32 v17, v21, v46
	v_fma_f32 v16, -v20, v17, v16
	v_div_fmas_f32 v16, v16, v46, v17
	v_div_fixup_f32 v12, v16, v12, 1.0
	v_pk_mul_f32 v[16:17], v[12:13], v[18:19] op_sel_hi:[1,0]
	s_nop 0
	v_mul_f32_e32 v12, 0x3fb8aa3b, v17
	v_fma_f32 v13, v17, s41, -v12
	v_rndne_f32_e32 v18, v12
	v_fmac_f32_e32 v13, 0x32a5705f, v17
	v_sub_f32_e32 v12, v12, v18
	v_add_f32_e32 v12, v12, v13
	v_exp_f32_e32 v20, v12
	v_cvt_i32_f32_e32 v18, v18
	v_cmp_ngt_f32_e32 vcc, s42, v17
	v_cmp_nlt_f32_e64 s[0:1], s43, v17
	ds_read2_b32 v[12:13], v35 offset0:162 offset1:178
	v_ldexp_f32 v18, v20, v18
	v_cndmask_b32_e32 v20, 0, v18, vcc
	v_pk_add_f32 v[18:19], v[16:17], v[16:17]
	v_cndmask_b32_e64 v17, v58, v20, s[0:1]
	v_mul_f32_e32 v21, 0x3fb8aa3b, v19
	v_rndne_f32_e32 v21, v21
	v_fmamk_f32 v29, v21, 0xbf317218, v19
	v_fmac_f32_e32 v29, 0x3102e308, v21
	v_fmamk_f32 v46, v29, 0x395133b1, v56
	v_fmaak_f32 v46, v29, v46, 0x3c0887f9
	v_fmaak_f32 v46, v29, v46, 0x3d2aaa81
	v_cvt_i32_f32_e32 v47, v21
	v_fmaak_f32 v46, v29, v46, 0x3e2aaaab
	v_fma_f32 v46, v29, v46, 0.5
	v_mul_f32_e32 v46, v29, v46
	v_fmac_f32_e32 v29, v29, v46
	v_ldexp_f32 v46, 1.0, v47
	v_cmp_eq_f32_e32 vcc, s44, v21
	ds_write_b32 v35, v17 offset:26504
	s_nop 0
	v_cndmask_b32_e32 v21, v46, v61, vcc
	v_add_f32_e32 v46, -1.0, v21
	v_fmac_f32_e32 v46, v21, v29
	v_add_f32_e32 v21, v46, v46
	v_cndmask_b32_e32 v21, v46, v21, vcc
	v_cmp_nlt_f32_e32 vcc, s45, v19
	s_nop 1
	v_cndmask_b32_e64 v21, v60, -v21, vcc
	v_mul_f32_e32 v29, 0x4f800000, v21
	v_cmp_gt_f32_e32 vcc, s46, v21
	s_nop 1
	v_cndmask_b32_e32 v21, v21, v29, vcc
	v_sqrt_f32_e32 v29, v21
	s_nop 0
	v_add_u32_e32 v17, -1, v29
	v_fma_f32 v20, -v17, v29, v21
	v_cmp_ge_f32_e64 s[0:1], 0, v20
	v_add_u32_e32 v20, 1, v29
	s_nop 0
	v_cndmask_b32_e64 v17, v29, v17, s[0:1]
	v_fma_f32 v29, -v20, v29, v21
	v_cmp_lt_f32_e64 s[0:1], 0, v29
	s_nop 1
	v_cndmask_b32_e64 v17, v17, v20, s[0:1]
	v_mul_f32_e32 v20, 0x37800000, v17
	v_cndmask_b32_e32 v17, v17, v20, vcc
	v_cmp_class_f32_e32 vcc, v21, v57
	v_cmp_nlt_f32_e64 s[0:1], s43, v16
	s_nop 0
	v_cndmask_b32_e32 v17, v17, v21, vcc
	v_cmp_ngt_f32_e32 vcc, s47, v19
	v_mul_f32_e32 v19, 0x3fb8aa3b, v16
	v_fma_f32 v20, v16, s41, -v19
	v_rndne_f32_e32 v21, v19
	v_cndmask_b32_e32 v17, 1.0, v17, vcc
	v_fmac_f32_e32 v20, 0x32a5705f, v16
	v_sub_f32_e32 v19, v19, v21
	v_add_f32_e32 v19, v19, v20
	v_mul_f32_e32 v10, v10, v17
	v_exp_f32_e32 v19, v19
	v_cvt_i32_f32_e32 v20, v21
	s_waitcnt lgkmcnt(1)
	v_mul_f32_e32 v10, v12, v10
	v_mul_f32_e32 v12, 0x3fb8aa3b, v18
	v_rndne_f32_e32 v12, v12
	v_fmamk_f32 v17, v12, 0xbf317218, v18
	v_fmac_f32_e32 v17, 0x3102e308, v12
	ds_write_b32 v35, v10 offset:43144
	v_ldexp_f32 v10, v19, v20
	v_fmamk_f32 v19, v17, 0x395133b1, v56
	v_fmaak_f32 v19, v17, v19, 0x3c0887f9
	v_fmaak_f32 v19, v17, v19, 0x3d2aaa81
	v_cvt_i32_f32_e32 v20, v12
	v_fmaak_f32 v19, v17, v19, 0x3e2aaaab
	v_fma_f32 v19, v17, v19, 0.5
	v_cmp_ngt_f32_e32 vcc, s42, v16
	v_mul_f32_e32 v19, v17, v19
	v_fmac_f32_e32 v17, v17, v19
	v_cndmask_b32_e32 v10, 0, v10, vcc
	v_ldexp_f32 v19, 1.0, v20
	v_cmp_eq_f32_e32 vcc, s44, v12
	v_cndmask_b32_e64 v10, v58, v10, s[0:1]
	ds_write_b32 v35, v10 offset:26764
	v_cndmask_b32_e32 v12, v19, v61, vcc
	v_add_f32_e32 v19, -1.0, v12
	v_fmac_f32_e32 v19, v12, v17
	v_add_f32_e32 v12, v19, v19
	v_cndmask_b32_e32 v12, v19, v12, vcc
	v_cmp_nlt_f32_e32 vcc, s45, v18
	s_nop 1
	v_cndmask_b32_e64 v12, v60, -v12, vcc
	v_mul_f32_e32 v17, 0x4f800000, v12
	v_cmp_gt_f32_e32 vcc, s46, v12
	s_nop 1
	v_cndmask_b32_e32 v12, v12, v17, vcc
	v_sqrt_f32_e32 v17, v12
	s_nop 0
	v_add_u32_e32 v10, -1, v17
	v_fma_f32 v16, -v10, v17, v12
	v_cmp_ge_f32_e64 s[0:1], 0, v16
	v_add_u32_e32 v16, 1, v17
	s_nop 0
	v_cndmask_b32_e64 v10, v17, v10, s[0:1]
	v_fma_f32 v17, -v16, v17, v12
	v_cmp_lt_f32_e64 s[0:1], 0, v17
	s_nop 1
	v_cndmask_b32_e64 v10, v10, v16, s[0:1]
	v_mul_f32_e32 v16, 0x37800000, v10
	v_cndmask_b32_e32 v10, v10, v16, vcc
	ds_read2_b32 v[16:17], v35 offset0:227 offset1:243
	v_cmp_class_f32_e32 vcc, v12, v57
	s_nop 1
	v_cndmask_b32_e32 v10, v10, v12, vcc
	v_cmp_ngt_f32_e32 vcc, s47, v18
	s_nop 1
	v_cndmask_b32_e32 v10, 1.0, v10, vcc
	v_mul_f32_e32 v10, v14, v10
	s_waitcnt lgkmcnt(0)
	v_mul_f32_e32 v10, v16, v10
	ds_write_b32 v35, v10 offset:43404
	s_nop 0
	s_waitcnt vmcnt(0) lgkmcnt(0)
	v_mov_b32_e32 v18, v164
	v_mov_b32_e32 v19, v165
	v_mov_b32_e32 v20, v166
	v_mov_b32_e32 v21, v167
	s_nop 1
	v_mfma_f32_16x16x32_bf16 v[18:21], v[6:9], v[18:21], 0
	s_nop 0
	s_nop 0
	s_nop 0
	s_nop 0
	s_nop 0
	s_nop 0
	s_waitcnt vmcnt(0) lgkmcnt(0)
	v_mov_b32_e32 v36, v168
	v_mov_b32_e32 v37, v169
	v_mov_b32_e32 v38, v170
	v_mov_b32_e32 v39, v171
	v_mov_b32_e32 v46, v172
	v_mov_b32_e32 v47, v173
	v_mov_b32_e32 v48, v174
	v_mov_b32_e32 v49, v175
	v_mov_b32_e32 v50, v176
	v_mov_b32_e32 v51, v177
	v_mov_b32_e32 v52, v178
	v_mov_b32_e32 v53, v179
	v_mov_b32_e32 v10, v186
	v_mov_b32_e32 v16, v187
	s_nop 1
	v_mfma_f32_16x16x32_bf16 v[46:49], v[6:9], v[46:49], 0
	s_nop 0
	v_mul_f32_e64 v14, |v10|, s31
	v_exp_f32_e32 v14, v14
	v_mfma_f32_16x16x32_bf16 v[6:9], v[2:5], v[36:39], v[18:21]
	v_max_f32_e64 v10, -v10, -v10
	v_max_f32_e32 v10, 0, v10
	s_nop 0
	v_add_f32_e32 v20, 1.0, v14
	v_add_f32_e32 v18, -1.0, v20
	v_sub_f32_e32 v19, v18, v20
	v_add_f32_e32 v19, 1.0, v19
	v_sub_f32_e32 v18, v14, v18
	v_add_f32_e32 v21, v18, v19
	v_frexp_mant_f32_e32 v26, v20
	v_cvt_f64_f32_e32 v[18:19], v20
	v_frexp_exp_i32_f64_e32 v18, v[18:19]
	v_cmp_gt_f32_e32 vcc, s33, v26
	v_mfma_f32_16x16x32_bf16 v[2:5], v[2:5], v[50:53], v[46:49]
	s_waitcnt vmcnt(0) lgkmcnt(0)
	v_mov_b32_e32 v12, v188
	v_add_f32_e32 v6, v6, v12
	v_subbrev_co_u32_e32 v26, vcc, 0, v18, vcc
	v_sub_u32_e32 v18, 0, v26
	v_ldexp_f32 v19, v20, v18
	v_add_f32_e32 v20, -1.0, v19
	v_add_f32_e32 v29, 1.0, v19
	v_ldexp_f32 v18, v21, v18
	v_add_f32_e32 v21, 1.0, v20
	v_add_f32_e32 v36, -1.0, v29
	v_sub_f32_e32 v21, v19, v21
	v_sub_f32_e32 v19, v19, v36
	v_add_f32_e32 v21, v18, v21
	v_add_f32_e32 v18, v18, v19
	v_add_f32_e32 v40, v29, v18
	v_rcp_f32_e32 v41, v40
	v_sub_f32_e32 v19, v40, v29
	v_sub_f32_e32 v29, v18, v19
	v_add_f32_e32 v19, v20, v21
	v_mul_f32_e32 v43, v19, v41
	v_sub_f32_e32 v18, v19, v20
	v_mul_f32_e32 v20, v40, v43
	v_fma_f32 v36, v43, v40, -v20
	v_fmac_f32_e32 v36, v43, v29
	v_sub_f32_e32 v42, v21, v18
	v_add_f32_e32 v18, v20, v36
	v_sub_f32_e32 v21, v19, v18
	v_pk_add_f32 v[38:39], v[18:19], v[20:21] neg_lo:[0,1] neg_hi:[0,1]
	v_mov_b32_e32 v37, v18
	v_pk_add_f32 v[18:19], v[38:39], v[36:37] neg_lo:[0,1] neg_hi:[0,1]
	v_add_f32_e32 v2, v2, v16
	v_add_f32_e32 v19, v42, v19
	v_add_f32_e32 v18, v18, v19
	v_add_f32_e32 v19, v21, v18
	v_mul_f32_e32 v42, v41, v19
	v_mul_f32_e32 v20, v40, v42
	v_fma_f32 v36, v42, v40, -v20
	v_fmac_f32_e32 v36, v42, v29
	v_sub_f32_e32 v21, v21, v19
	v_add_f32_e32 v29, v18, v21
	v_add_f32_e32 v18, v20, v36
	v_sub_f32_e32 v21, v19, v18
	v_pk_add_f32 v[38:39], v[18:19], v[20:21] neg_lo:[0,1] neg_hi:[0,1]
	v_mov_b32_e32 v37, v18
	v_pk_add_f32 v[18:19], v[38:39], v[36:37] neg_lo:[0,1] neg_hi:[0,1]
	v_cmp_neq_f32_e32 vcc, s35, v14
	v_add_f32_e32 v19, v29, v19
	v_add_f32_e32 v18, v18, v19
	v_add_f32_e32 v19, v43, v42
	v_add_f32_e32 v18, v21, v18
	v_sub_f32_e32 v20, v19, v43
	v_mul_f32_e32 v18, v41, v18
	v_sub_f32_e32 v20, v42, v20
	v_add_f32_e32 v20, v20, v18
	v_add_f32_e32 v36, v19, v20
	v_mul_f32_e32 v37, v36, v36
	v_fmamk_f32 v18, v37, 0x3e9b6dac, v1
	v_fmaak_f32 v29, v37, v18, 0x3f2aaada
	v_cvt_f32_i32_e32 v18, v26
	v_sub_f32_e32 v19, v36, v19
	v_sub_f32_e32 v19, v20, v19
	v_ldexp_f32 v26, v19, 1
	v_mul_f32_e32 v19, v36, v37
	v_ldexp_f32 v21, v36, 1
	v_pk_mul_f32 v[36:37], v[18:19], v[28:29]
	v_mul_f32_e32 v2, 0xbfb8aa3b, v2
	v_fma_f32 v20, v18, s34, -v36
	v_fmac_f32_e32 v20, 0xb102e308, v18
	v_pk_add_f32 v[18:19], v[36:37], v[20:21]
	v_mov_b32_e32 v38, v36
	v_sub_f32_e32 v21, v19, v21
	v_sub_f32_e32 v21, v37, v21
	v_add_f32_e32 v39, v26, v21
	v_pk_add_f32 v[36:37], v[18:19], v[36:37] neg_lo:[0,1] neg_hi:[0,1]
	v_pk_add_f32 v[40:41], v[18:19], v[38:39]
	v_mov_b32_e32 v21, v18
	v_mov_b32_e32 v37, v41
	v_pk_add_f32 v[42:43], v[20:21], v[36:37] neg_lo:[0,1] neg_hi:[0,1]
	v_pk_add_f32 v[20:21], v[20:21], v[36:37]
	v_mov_b32_e32 v38, v39
	v_pk_add_f32 v[36:37], v[20:21], v[18:19] op_sel:[1,0] op_sel_hi:[0,1] neg_lo:[0,1] neg_hi:[0,1]
	v_pk_add_f32 v[44:45], v[40:41], v[36:37] op_sel_hi:[1,0] neg_lo:[0,1] neg_hi:[0,1]
	v_mov_b32_e32 v40, v41
	v_mov_b32_e32 v41, v21
	v_pk_mov_b32 v[36:37], v[18:19], v[36:37] op_sel:[1,0]
	v_mov_b32_e32 v39, v18
	v_pk_add_f32 v[36:37], v[40:41], v[36:37] neg_lo:[0,1] neg_hi:[0,1]
	v_mov_b32_e32 v44, v42
	v_pk_add_f32 v[18:19], v[38:39], v[36:37] neg_lo:[0,1] neg_hi:[0,1]
	v_mov_b32_e32 v43, v21
	v_pk_add_f32 v[36:37], v[44:45], v[18:19]
	v_exp_f32_e32 v2, v2
	v_pk_add_f32 v[38:39], v[36:37], v[36:37] op_sel:[0,1] op_sel_hi:[1,0]
	v_add_f32_e32 v3, v3, v16
	v_pk_add_f32 v[20:21], v[20:21], v[38:39] op_sel:[1,0] op_sel_hi:[0,1]
	v_mov_b32_e32 v37, v20
	v_pk_add_f32 v[40:41], v[36:37], v[42:43] neg_lo:[0,1] neg_hi:[0,1]
	v_mov_b32_e32 v19, v38
	v_sub_f32_e32 v21, v36, v40
	v_pk_add_f32 v[18:19], v[18:19], v[40:41] neg_lo:[0,1] neg_hi:[0,1]
	v_sub_f32_e32 v21, v42, v21
	v_add_f32_e32 v18, v18, v21
	v_add_f32_e32 v18, v18, v19
	v_add_f32_e32 v18, v20, v18
	v_cndmask_b32_e32 v18, v58, v18, vcc
	v_cmp_ngt_f32_e32 vcc, -1.0, v14
	v_mul_f32_e32 v6, 0xbfb8aa3b, v6
	v_mul_f32_e32 v3, 0xbfb8aa3b, v3
	v_cndmask_b32_e32 v18, v59, v18, vcc
	v_cmp_neq_f32_e32 vcc, -1.0, v14
	v_exp_f32_e32 v19, v6
	v_exp_f32_e32 v3, v3
	v_cndmask_b32_e32 v18, v60, v18, vcc
	v_cmp_lt_f32_e64 vcc, |v14|, s36
	v_add_f32_e32 v4, v4, v16
	v_mul_f32_e32 v4, 0xbfb8aa3b, v4
	v_cndmask_b32_e32 v14, v18, v14, vcc
	v_add_f32_e32 v10, v10, v14
	v_add_f32_e32 v14, 1.0, v2
	v_div_scale_f32 v2, s[0:1], v14, v14, 1.0
	v_rcp_f32_e32 v18, v2
	v_mul_f32_e32 v10, 0xc1000000, v10
	v_exp_f32_e32 v4, v4
	v_add_f32_e32 v5, v5, v16
	v_fma_f32 v6, -v2, v18, 1.0
	v_fmac_f32_e32 v18, v6, v18
	v_div_scale_f32 v6, vcc, 1.0, v14, 1.0
	v_mul_f32_e32 v20, v6, v18
	v_fma_f32 v21, -v2, v20, v6
	v_fmac_f32_e32 v20, v21, v18
	v_add_f32_e32 v21, 1.0, v3
	v_fma_f32 v2, -v2, v20, v6
	v_div_scale_f32 v6, s[0:1], v21, v21, 1.0
	v_rcp_f32_e32 v26, v6
	v_div_fmas_f32 v20, v2, v18, v20
	v_add_f32_e32 v2, v7, v12
	v_mul_f32_e32 v2, 0xbfb8aa3b, v2
	v_exp_f32_e32 v18, v2
	v_fma_f32 v2, -v6, v26, 1.0
	v_fmac_f32_e32 v26, v2, v26
	v_div_scale_f32 v7, vcc, 1.0, v21, 1.0
	v_mul_f32_e32 v29, v7, v26
	v_fma_f32 v2, -v6, v29, v7
	v_fmac_f32_e32 v29, v2, v26
	v_pk_add_f32 v[2:3], v[18:19], 1.0 op_sel_hi:[1,0]
	v_fma_f32 v6, -v6, v29, v7
	v_div_scale_f32 v18, s[0:1], v3, v3, 1.0
	v_rcp_f32_e32 v19, v18
	v_div_fmas_f32 v26, v6, v26, v29
	v_div_fixup_f32 v14, v20, v14, 1.0
	v_div_fixup_f32 v20, v26, v21, 1.0
	v_fma_f32 v6, -v18, v19, 1.0
	v_fmac_f32_e32 v19, v6, v19
	v_div_scale_f32 v6, vcc, 1.0, v3, 1.0
	v_mul_f32_e32 v7, v6, v19
	v_fma_f32 v29, -v18, v7, v6
	v_fmac_f32_e32 v7, v29, v19
	v_fma_f32 v6, -v18, v7, v6
	v_div_scale_f32 v18, s[0:1], v2, v2, 1.0
	v_rcp_f32_e32 v29, v18
	v_div_fmas_f32 v6, v6, v19, v7
	v_div_fixup_f32 v3, v6, v3, 1.0
	v_mul_f32_e32 v5, 0xbfb8aa3b, v5
	v_fma_f32 v6, -v18, v29, 1.0
	v_fmac_f32_e32 v29, v6, v29
	v_div_scale_f32 v6, vcc, 1.0, v2, 1.0
	v_mul_f32_e32 v7, v6, v29
	v_fma_f32 v19, -v18, v7, v6
	v_fmac_f32_e32 v7, v19, v29
	v_fma_f32 v6, -v18, v7, v6
	v_div_fmas_f32 v6, v6, v29, v7
	v_div_fixup_f32 v2, v6, v2, 1.0
	v_pk_mul_f32 v[6:7], v[2:3], v[10:11] op_sel_hi:[1,0]
	v_exp_f32_e32 v5, v5
	v_mul_f32_e32 v2, 0x3fb8aa3b, v7
	v_fma_f32 v3, v7, s41, -v2
	v_rndne_f32_e32 v18, v2
	v_fmac_f32_e32 v3, 0x32a5705f, v7
	v_sub_f32_e32 v2, v2, v18
	v_add_f32_e32 v2, v2, v3
	v_exp_f32_e32 v3, v2
	v_cvt_i32_f32_e32 v18, v18
	v_cmp_ngt_f32_e32 vcc, s42, v7
	v_cmp_nlt_f32_e64 s[0:1], s43, v7
	v_and_b32_e32 v2, 63, v30
	v_ldexp_f32 v3, v3, v18
	v_pk_add_f32 v[18:19], v[6:7], v[6:7]
	v_cndmask_b32_e32 v3, 0, v3, vcc
	v_mul_f32_e32 v21, 0x3fb8aa3b, v19
	v_rndne_f32_e32 v21, v21
	v_fmamk_f32 v26, v21, 0xbf317218, v19
	v_fmac_f32_e32 v26, 0x3102e308, v21
	v_fmamk_f32 v29, v26, 0x395133b1, v56
	v_fmaak_f32 v29, v26, v29, 0x3c0887f9
	v_fmaak_f32 v29, v26, v29, 0x3d2aaa81
	v_cvt_i32_f32_e32 v36, v21
	v_fmaak_f32 v29, v26, v29, 0x3e2aaaab
	v_fma_f32 v29, v26, v29, 0.5
	v_mul_f32_e32 v29, v26, v29
	v_fmac_f32_e32 v26, v26, v29
	v_ldexp_f32 v29, 1.0, v36
	v_cmp_eq_f32_e32 vcc, s44, v21
	v_cndmask_b32_e64 v3, v58, v3, s[0:1]
	ds_write_b32 v35, v3 offset:26048
	v_cndmask_b32_e32 v21, v29, v61, vcc
	v_add_f32_e32 v29, -1.0, v21
	v_fmac_f32_e32 v29, v21, v26
	v_add_f32_e32 v21, v29, v29
	v_cndmask_b32_e32 v21, v29, v21, vcc
	v_cmp_nlt_f32_e32 vcc, s45, v19
	s_nop 1
	v_cndmask_b32_e64 v21, v60, -v21, vcc
	v_mul_f32_e32 v26, 0x4f800000, v21
	v_cmp_gt_f32_e32 vcc, s46, v21
	s_nop 1
	v_cndmask_b32_e32 v21, v21, v26, vcc
	v_sqrt_f32_e32 v26, v21
	s_nop 0
	v_add_u32_e32 v3, -1, v26
	v_fma_f32 v7, -v3, v26, v21
	v_cmp_ge_f32_e64 s[0:1], 0, v7
	v_add_u32_e32 v7, 1, v26
	s_nop 0
	v_cndmask_b32_e64 v3, v26, v3, s[0:1]
	v_fma_f32 v26, -v7, v26, v21
	v_cmp_lt_f32_e64 s[0:1], 0, v26
	s_nop 1
	v_cndmask_b32_e64 v3, v3, v7, s[0:1]
	v_mul_f32_e32 v7, 0x37800000, v3
	v_cndmask_b32_e32 v3, v3, v7, vcc
	v_cmp_class_f32_e32 vcc, v21, v57
	v_mul_f32_e32 v7, 0x3fb8aa3b, v6
	v_cmp_nlt_f32_e64 s[0:1], s43, v6
	v_cndmask_b32_e32 v3, v3, v21, vcc
	v_cmp_ngt_f32_e32 vcc, s47, v19
	v_fma_f32 v19, v6, s41, -v7
	v_rndne_f32_e32 v21, v7
	v_fmac_f32_e32 v19, 0x32a5705f, v6
	v_sub_f32_e32 v7, v7, v21
	v_add_f32_e32 v7, v7, v19
	v_exp_f32_e32 v7, v7
	v_cvt_i32_f32_e32 v19, v21
	v_cndmask_b32_e32 v3, 1.0, v3, vcc
	v_mul_f32_e32 v3, v14, v3
	v_mul_f32_e32 v3, v11, v3
	ds_write_b32 v35, v3 offset:42688
	v_ldexp_f32 v3, v7, v19
	v_mul_f32_e32 v7, 0x3fb8aa3b, v18
	v_rndne_f32_e32 v7, v7
	v_fmamk_f32 v11, v7, 0xbf317218, v18
	v_fmac_f32_e32 v11, 0x3102e308, v7
	v_fmamk_f32 v14, v11, 0x395133b1, v56
	v_fmaak_f32 v14, v11, v14, 0x3c0887f9
	v_fmaak_f32 v14, v11, v14, 0x3d2aaa81
	v_cvt_i32_f32_e32 v19, v7
	v_fmaak_f32 v14, v11, v14, 0x3e2aaaab
	v_fma_f32 v14, v11, v14, 0.5
	v_cmp_ngt_f32_e32 vcc, s42, v6
	v_mul_f32_e32 v14, v11, v14
	v_fmac_f32_e32 v11, v11, v14
	v_cndmask_b32_e32 v3, 0, v3, vcc
	v_ldexp_f32 v14, 1.0, v19
	v_cmp_eq_f32_e32 vcc, s44, v7
	v_cndmask_b32_e64 v3, v58, v3, s[0:1]
	ds_write_b32 v35, v3 offset:26308
	v_cndmask_b32_e32 v7, v14, v61, vcc
	v_add_f32_e32 v14, -1.0, v7
	v_fmac_f32_e32 v14, v7, v11
	v_add_f32_e32 v7, v14, v14
	v_cndmask_b32_e32 v7, v14, v7, vcc
	v_cmp_nlt_f32_e32 vcc, s45, v18
	s_nop 1
	v_cndmask_b32_e64 v7, v60, -v7, vcc
	v_mul_f32_e32 v11, 0x4f800000, v7
	v_cmp_gt_f32_e32 vcc, s46, v7
	s_nop 1
	v_cndmask_b32_e32 v7, v7, v11, vcc
	v_sqrt_f32_e32 v11, v7
	s_nop 0
	v_add_u32_e32 v3, -1, v11
	v_fma_f32 v6, -v3, v11, v7
	v_cmp_ge_f32_e64 s[0:1], 0, v6
	v_add_u32_e32 v6, 1, v11
	s_nop 0
	v_cndmask_b32_e64 v3, v11, v3, s[0:1]
	v_fma_f32 v11, -v6, v11, v7
	v_cmp_lt_f32_e64 s[0:1], 0, v11
	v_add_f32_e32 v11, 1.0, v4
	s_nop 0
	v_cndmask_b32_e64 v3, v3, v6, s[0:1]
	v_mul_f32_e32 v6, 0x37800000, v3
	v_div_scale_f32 v4, s[0:1], v11, v11, 1.0
	v_cndmask_b32_e32 v3, v3, v6, vcc
	v_rcp_f32_e32 v6, v4
	v_cmp_class_f32_e32 vcc, v7, v57
	s_nop 1
	v_cndmask_b32_e32 v3, v3, v7, vcc
	v_cmp_ngt_f32_e32 vcc, s47, v18
	v_add_f32_e32 v7, v8, v12
	v_fma_f32 v8, -v4, v6, 1.0
	v_cndmask_b32_e32 v3, 1.0, v3, vcc
	v_fmac_f32_e32 v6, v8, v6
	v_div_scale_f32 v8, vcc, 1.0, v11, 1.0
	v_mul_f32_e32 v3, v20, v3
	v_mul_f32_e32 v14, v8, v6
	v_mul_f32_e32 v3, v15, v3
	v_fma_f32 v15, -v4, v14, v8
	v_fmac_f32_e32 v14, v15, v6
	v_fma_f32 v4, -v4, v14, v8
	v_div_fmas_f32 v8, v4, v6, v14
	v_add_f32_e32 v14, 1.0, v5
	v_div_scale_f32 v15, s[0:1], v14, v14, 1.0
	v_rcp_f32_e32 v16, v15
	v_add_f32_e32 v4, v9, v12
	v_mul_f32_e32 v7, 0xbfb8aa3b, v7
	v_mul_f32_e32 v4, 0xbfb8aa3b, v4
	v_exp_f32_e32 v7, v7
	v_exp_f32_e32 v6, v4
	v_fma_f32 v4, -v15, v16, 1.0
	v_fmac_f32_e32 v16, v4, v16
	v_div_scale_f32 v9, vcc, 1.0, v14, 1.0
	v_mul_f32_e32 v12, v9, v16
	v_fma_f32 v4, -v15, v12, v9
	v_fmac_f32_e32 v12, v4, v16
	v_pk_add_f32 v[4:5], v[6:7], 1.0 op_sel_hi:[1,0]
	v_fma_f32 v9, -v15, v12, v9
	v_div_scale_f32 v6, s[0:1], v5, v5, 1.0
	v_rcp_f32_e32 v7, v6
	v_div_fmas_f32 v9, v9, v16, v12
	ds_write_b32 v35, v3 offset:42948
	v_div_fixup_f32 v3, v8, v11, 1.0
	v_fma_f32 v12, -v6, v7, 1.0
	v_fmac_f32_e32 v7, v12, v7
	v_div_scale_f32 v12, vcc, 1.0, v5, 1.0
	v_mul_f32_e32 v15, v12, v7
	v_fma_f32 v16, -v6, v15, v12
	v_fmac_f32_e32 v15, v16, v7
	v_fma_f32 v6, -v6, v15, v12
	v_div_scale_f32 v12, s[0:1], v4, v4, 1.0
	v_rcp_f32_e32 v16, v12
	v_div_fmas_f32 v6, v6, v7, v15
	v_div_fixup_f32 v5, v6, v5, 1.0
	v_div_fixup_f32 v8, v9, v14, 1.0
	v_fma_f32 v6, -v12, v16, 1.0
	v_fmac_f32_e32 v16, v6, v16
	v_div_scale_f32 v6, vcc, 1.0, v4, 1.0
	v_mul_f32_e32 v7, v6, v16
	v_fma_f32 v15, -v12, v7, v6
	v_fmac_f32_e32 v7, v15, v16
	v_fma_f32 v6, -v12, v7, v6
	v_div_fmas_f32 v6, v6, v16, v7
	v_div_fixup_f32 v4, v6, v4, 1.0
	v_pk_mul_f32 v[4:5], v[4:5], v[10:11] op_sel_hi:[1,0]
	s_nop 0
	v_mul_f32_e32 v6, 0x3fb8aa3b, v5
	v_fma_f32 v7, v5, s41, -v6
	v_rndne_f32_e32 v10, v6
	v_fmac_f32_e32 v7, 0x32a5705f, v5
	v_sub_f32_e32 v6, v6, v10
	v_add_f32_e32 v6, v6, v7
	v_exp_f32_e32 v6, v6
	v_cvt_i32_f32_e32 v7, v10
	v_cmp_ngt_f32_e32 vcc, s42, v5
	v_cmp_nlt_f32_e64 s[0:1], s43, v5
	v_ldexp_f32 v6, v6, v7
	v_cndmask_b32_e32 v9, 0, v6, vcc
	v_pk_add_f32 v[6:7], v[4:5], v[4:5]
	v_cndmask_b32_e64 v5, v58, v9, s[0:1]
	v_mul_f32_e32 v10, 0x3fb8aa3b, v7
	v_rndne_f32_e32 v10, v10
	v_fmamk_f32 v11, v10, 0xbf317218, v7
	v_fmac_f32_e32 v11, 0x3102e308, v10
	v_fmamk_f32 v12, v11, 0x395133b1, v56
	v_fmaak_f32 v12, v11, v12, 0x3c0887f9
	v_fmaak_f32 v12, v11, v12, 0x3d2aaa81
	v_cvt_i32_f32_e32 v14, v10
	v_fmaak_f32 v12, v11, v12, 0x3e2aaaab
	v_fma_f32 v12, v11, v12, 0.5
	v_mul_f32_e32 v12, v11, v12
	v_fmac_f32_e32 v11, v11, v12
	v_ldexp_f32 v12, 1.0, v14
	v_cmp_eq_f32_e32 vcc, s44, v10
	ds_write_b32 v35, v5 offset:26568
	s_nop 0
	v_cndmask_b32_e32 v10, v12, v61, vcc
	v_add_f32_e32 v12, -1.0, v10
	v_fmac_f32_e32 v12, v10, v11
	v_add_f32_e32 v10, v12, v12
	v_cndmask_b32_e32 v10, v12, v10, vcc
	v_cmp_nlt_f32_e32 vcc, s45, v7
	s_nop 1
	v_cndmask_b32_e64 v10, v60, -v10, vcc
	v_mul_f32_e32 v11, 0x4f800000, v10
	v_cmp_gt_f32_e32 vcc, s46, v10
	s_nop 1
	v_cndmask_b32_e32 v10, v10, v11, vcc
	v_sqrt_f32_e32 v11, v10
	s_nop 0
	v_add_u32_e32 v5, -1, v11
	v_fma_f32 v9, -v5, v11, v10
	v_cmp_ge_f32_e64 s[0:1], 0, v9
	v_add_u32_e32 v9, 1, v11
	s_nop 0
	v_cndmask_b32_e64 v5, v11, v5, s[0:1]
	v_fma_f32 v11, -v9, v11, v10
	v_cmp_lt_f32_e64 s[0:1], 0, v11
	s_nop 1
	v_cndmask_b32_e64 v5, v5, v9, s[0:1]
	v_mul_f32_e32 v9, 0x37800000, v5
	v_cndmask_b32_e32 v5, v5, v9, vcc
	v_cmp_class_f32_e32 vcc, v10, v57
	v_cmp_nlt_f32_e64 s[0:1], s43, v4
	s_nop 0
	v_cndmask_b32_e32 v5, v5, v10, vcc
	v_cmp_ngt_f32_e32 vcc, s47, v7
	v_mul_f32_e32 v7, 0x3fb8aa3b, v4
	v_fma_f32 v9, v4, s41, -v7
	v_rndne_f32_e32 v10, v7
	v_fmac_f32_e32 v9, 0x32a5705f, v4
	v_sub_f32_e32 v7, v7, v10
	v_add_f32_e32 v7, v7, v9
	v_exp_f32_e32 v7, v7
	v_cvt_i32_f32_e32 v9, v10
	v_cndmask_b32_e32 v5, 1.0, v5, vcc
	v_mul_f32_e32 v3, v3, v5
	v_mul_f32_e32 v5, 0x3fb8aa3b, v6
	v_mul_f32_e32 v3, v13, v3
	v_rndne_f32_e32 v5, v5
	ds_write_b32 v35, v3 offset:43208
	v_ldexp_f32 v3, v7, v9
	v_fmamk_f32 v7, v5, 0xbf317218, v6
	v_fmac_f32_e32 v7, 0x3102e308, v5
	v_fmamk_f32 v9, v7, 0x395133b1, v56
	v_fmaak_f32 v9, v7, v9, 0x3c0887f9
	v_fmaak_f32 v9, v7, v9, 0x3d2aaa81
	v_cvt_i32_f32_e32 v10, v5
	v_fmaak_f32 v9, v7, v9, 0x3e2aaaab
	v_fma_f32 v9, v7, v9, 0.5
	v_cmp_ngt_f32_e32 vcc, s42, v4
	v_mul_f32_e32 v9, v7, v9
	v_fmac_f32_e32 v7, v7, v9
	v_cndmask_b32_e32 v3, 0, v3, vcc
	v_ldexp_f32 v9, 1.0, v10
	v_cmp_eq_f32_e32 vcc, s44, v5
	v_cndmask_b32_e64 v3, v58, v3, s[0:1]
	ds_write_b32 v35, v3 offset:26828
	v_cndmask_b32_e32 v5, v9, v61, vcc
	v_add_f32_e32 v9, -1.0, v5
	v_fmac_f32_e32 v9, v5, v7
	v_add_f32_e32 v5, v9, v9
	v_cndmask_b32_e32 v5, v9, v5, vcc
	v_cmp_nlt_f32_e32 vcc, s45, v6
	s_nop 1
	v_cndmask_b32_e64 v5, v60, -v5, vcc
	v_mul_f32_e32 v7, 0x4f800000, v5
	v_cmp_gt_f32_e32 vcc, s46, v5
	s_nop 1
	v_cndmask_b32_e32 v5, v5, v7, vcc
	v_sqrt_f32_e32 v7, v5
	s_nop 0
	v_add_u32_e32 v3, -1, v7
	v_fma_f32 v4, -v3, v7, v5
	v_cmp_ge_f32_e64 s[0:1], 0, v4
	v_add_u32_e32 v4, 1, v7
	s_nop 0
	v_cndmask_b32_e64 v3, v7, v3, s[0:1]
	v_fma_f32 v7, -v4, v7, v5
	v_cmp_lt_f32_e64 s[0:1], 0, v7
	s_nop 1
	v_cndmask_b32_e64 v3, v3, v4, s[0:1]
	v_mul_f32_e32 v4, 0x37800000, v3
	v_cndmask_b32_e32 v3, v3, v4, vcc
	v_cmp_class_f32_e32 vcc, v5, v57
	s_nop 1
	v_cndmask_b32_e32 v3, v3, v5, vcc
	v_cmp_ngt_f32_e32 vcc, s47, v6
	s_nop 1
	v_cndmask_b32_e32 v3, 1.0, v3, vcc
	v_mul_f32_e32 v3, v8, v3
	v_mul_f32_e32 v3, v17, v3
	v_mad_u64_u32 v[4:5], s[0:1], v31, s37, v[2:3]
	ds_write_b32 v35, v3 offset:43468
	v_lshl_add_u32 v3, v4, 2, 0
	v_add_u32_e32 v4, 0x6400, v3
	v_add_u32_e32 v6, 0xa400, v3
	s_waitcnt lgkmcnt(0)
	s_barrier
	ds_read2_b32 v[4:5], v4 offset0:64 offset1:129
	ds_read2_b32 v[6:7], v6 offset0:128 offset1:193
	v_add_u32_e32 v8, 0x6600, v3
	v_add_u32_e32 v12, 0xa800, v3
	ds_read2_b32 v[8:9], v8 offset0:66 offset1:131
	ds_read2_b32 v[10:11], v12 offset0:2 offset1:67
	s_waitcnt lgkmcnt(2)
	v_fma_f32 v6, 0, v4, v6
	v_fmac_f32_e32 v7, v6, v5
	v_mul_f32_e32 v4, v4, v5
	v_add_u32_e32 v26, 0xb000, v3
	s_waitcnt lgkmcnt(0)
	v_fma_f32 v5, v7, v8, v10
	v_fmac_f32_e32 v11, v5, v9
	v_add_u32_e32 v5, 0x6800, v3
	ds_read2_b32 v[6:7], v5 offset0:68 offset1:133
	ds_read2_b32 v[12:13], v12 offset0:132 offset1:197
	v_add_u32_e32 v5, 0x6a00, v3
	ds_read2_b32 v[14:15], v5 offset0:70 offset1:135
	v_add_u32_e32 v5, 0xac00, v3
	ds_read2_b32 v[16:17], v5 offset0:6 offset1:71
	v_add_u32_e32 v10, 0x6c00, v3
	ds_read2_b32 v[18:19], v10 offset0:72 offset1:137
	ds_read2_b32 v[20:21], v5 offset0:136 offset1:201
	s_waitcnt lgkmcnt(4)
	v_fma_f32 v5, v11, v6, v12
	v_fmac_f32_e32 v13, v5, v7
	s_waitcnt lgkmcnt(2)
	v_fma_f32 v5, v13, v14, v16
	v_fmac_f32_e32 v17, v5, v15
	v_add_u32_e32 v5, 0x6e00, v3
	ds_read2_b32 v[10:11], v5 offset0:74 offset1:139
	ds_read2_b32 v[12:13], v26 offset0:10 offset1:75
	s_waitcnt lgkmcnt(2)
	v_fmac_f32_e32 v20, v17, v18
	v_mov_b32_e32 v5, v20
	v_mov_b32_e32 v16, v8
	v_mov_b32_e32 v17, v19
	v_mov_b32_e32 v20, v9
	v_mul_f32_e32 v8, v4, v8
	v_pk_fma_f32 v[4:5], v[4:5], v[16:17], v[20:21]
	v_mul_f32_e32 v8, v8, v9
	v_mov_b32_e32 v9, v5
	v_mov_b32_e32 v4, v6
	s_waitcnt lgkmcnt(1)
	v_mov_b32_e32 v5, v10
	v_pk_mul_f32 v[16:17], v[8:9], v[4:5]
	v_mov_b32_e32 v6, v7
	v_mov_b32_e32 v20, v7
	s_waitcnt lgkmcnt(0)
	v_mov_b32_e32 v21, v12
	v_pk_mul_f32 v[6:7], v[16:17], v[6:7]
	v_pk_fma_f32 v[4:5], v[8:9], v[4:5], v[20:21]
	v_add_u32_e32 v8, 0x7000, v3
	v_mov_b32_e32 v4, v6
	ds_read2_b32 v[8:9], v8 offset0:76 offset1:141
	ds_read2_b32 v[16:17], v26 offset0:140 offset1:205
	ds_read_b32 v21, v3 offset:29496
	ds_read_b32 v35, v3 offset:46136
	v_mov_b32_e32 v38, v14
	v_mov_b32_e32 v39, v11
	v_pk_mul_f32 v[6:7], v[6:7], v[14:15]
	v_mov_b32_e32 v14, v15
	v_mov_b32_e32 v12, v15
	v_pk_mul_f32 v[6:7], v[6:7], v[14:15]
	v_pk_fma_f32 v[4:5], v[4:5], v[38:39], v[12:13]
	v_or_b32_e32 v3, 15, v34
	v_mov_b32_e32 v7, v5
	v_mov_b32_e32 v4, v18
	s_waitcnt lgkmcnt(3)
	v_mov_b32_e32 v5, v8
	v_mad_u64_u32 v[2:3], s[0:1], v3, s37, v[2:3]
	v_pk_mul_f32 v[12:13], v[6:7], v[4:5]
	v_mov_b32_e32 v14, v19
	v_mov_b32_e32 v18, v19
	s_waitcnt lgkmcnt(2)
	v_mov_b32_e32 v19, v16
	v_lshl_add_u32 v2, v2, 2, 0
	v_pk_mul_f32 v[12:13], v[12:13], v[14:15]
	v_pk_fma_f32 v[4:5], v[6:7], v[4:5], v[18:19]
	ds_read2st64_b32 v[36:37], v2 offset0:101 offset1:166
	v_mov_b32_e32 v4, v12
	v_mov_b32_e32 v6, v10
	v_mov_b32_e32 v7, v9
	v_pk_mul_f32 v[12:13], v[12:13], v[10:11]
	v_mov_b32_e32 v10, v11
	v_mov_b32_e32 v16, v11
	v_pk_mul_f32 v[10:11], v[12:13], v[10:11]
	v_pk_fma_f32 v[4:5], v[4:5], v[6:7], v[16:17]
	v_mov_b32_e32 v20, v8
	v_mov_b32_e32 v11, v5
	s_waitcnt lgkmcnt(2)
	v_pk_mul_f32 v[4:5], v[10:11], v[20:21]
	v_mov_b32_e32 v6, v9
	v_mov_b32_e32 v34, v9
	v_pk_mul_f32 v[4:5], v[4:5], v[6:7]
	s_waitcnt lgkmcnt(1)
	v_pk_fma_f32 v[6:7], v[10:11], v[20:21], v[34:35]
	v_mov_b32_e32 v8, v21
	v_mov_b32_e32 v6, v4
	v_mov_b32_e32 v10, v21
	s_waitcnt lgkmcnt(0)
	v_mov_b32_e32 v11, v36
	v_pk_mul_f32 v[4:5], v[4:5], v[8:9]
	v_pk_fma_f32 v[6:7], v[6:7], v[10:11], v[36:37]
	v_pk_mul_f32 v[4:5], v[4:5], v[36:37]
	v_lshl_add_u32 v2, v30, 3, 0
	v_mov_b32_e32 v5, v7
	v_cmp_gt_i32_e32 vcc, 64, v30
	ds_write_b64 v2, v[4:5] offset:61184
	s_waitcnt lgkmcnt(0)
	s_barrier
	s_and_saveexec_b64 s[0:1], vcc
	s_cbranch_execz .LBB0_1072
	v_add_u32_e32 v6, 0x100, v2
	ds_read2st64_b64 v[2:5], v6 offset0:119 offset1:120
	ds_read2st64_b64 v[6:9], v6 offset0:121 offset1:122
	s_lshl_b32 s16, s22, 7
	s_or_b32 s22, s16, s50
	s_ashr_i32 s23, s22, 31
	s_waitcnt lgkmcnt(1)
	v_fma_f32 v3, 0, v2, v3
	v_fmac_f32_e32 v5, v3, v4
	s_lshl_b64 s[22:23], s[22:23], 12
	v_mul_f32_e32 v2, v2, v4
	s_waitcnt lgkmcnt(0)
	v_fma_f32 v3, v5, v6, v7
	v_lshl_add_u64 v[4:5], v[32:33], 0, s[22:23]
	s_lshl_b32 s16, s49, 3
	v_ashrrev_i32_e32 v31, 31, v30
	v_lshl_add_u64 v[4:5], v[4:5], 0, s[16:17]
	v_mov_b32_e32 v7, v8
	v_lshl_add_u64 v[4:5], v[30:31], 3, v[4:5]
	v_pk_mul_f32 v[10:11], v[2:3], v[6:7]
	v_pk_fma_f32 v[2:3], v[2:3], v[6:7], v[8:9]
	v_pk_mul_f32 v[10:11], v[10:11], v[8:9]
	v_add_co_u32_e32 v2, vcc, 0x2d100000, v4
	v_mov_b32_e32 v11, v3
	s_nop 0
	v_addc_co_u32_e32 v3, vcc, 0, v5, vcc
	flat_store_dwordx2 v[2:3], v[10:11]
	s_branch .LBB0_1072
